# plus P7 Hyena: L2 touch-prefetch of gate rows before each product, tail vmcnt(0)->vmcnt(16) after output stores
# baseline (speedup 1.0000x reference)
.LBB0_2203:
	s_or_b64 exec, exec, s[16:17]
	s_add_i32 s20, s12, 0x200
	s_ashr_i32 s20, s20, 3
	s_ashr_i32 s21, s20, 31
	s_lshl_b64 s[20:21], s[20:21], 7
	s_and_b32 s32, s12, 7
	v_mov_b32_e32 v244, s32
	v_or3_b32 v244, s20, v140, v244
	v_mov_b32_e32 v245, s21
	v_lshlrev_b64 v[244:245], 12, v[244:245]
	v_lshl_add_u64 v[244:245], v[160:161], 0, v[244:245]
	global_load_dword v233, v[244:245], off
	global_load_dword v233, v[244:245], off offset:64
	global_load_dword v233, v[244:245], off offset:128
	global_load_dword v233, v[244:245], off offset:192
	global_load_dword v233, v[244:245], off offset:256
	global_load_dword v233, v[244:245], off offset:320
	global_load_dword v233, v[244:245], off offset:384
	global_load_dword v233, v[244:245], off offset:448
	global_load_dword v233, v[244:245], off offset:512
	global_load_dword v233, v[244:245], off offset:576
	global_load_dword v233, v[244:245], off offset:640
	global_load_dword v233, v[244:245], off offset:704
	global_load_dword v233, v[244:245], off offset:768
	global_load_dword v233, v[244:245], off offset:832
	global_load_dword v233, v[244:245], off offset:896
	global_load_dword v233, v[244:245], off offset:960
	ds_read2_b32 v[6:7], v179 offset1:1
	ds_read2_b32 v[10:11], v178 offset1:1
	ds_read2_b32 v[18:19], v177 offset1:1
	ds_read2_b32 v[14:15], v181 offset1:1
	ds_read2_b32 v[16:17], v182 offset1:1
	s_waitcnt lgkmcnt(0)
	v_alignbit_b32 v13, v7, v6, v3
	v_alignbit_b32 v12, v6, v11, v4
	ds_read_b128 v[6:9], v5 offset:896
	v_alignbit_b32 v11, v11, v19, v1
	v_alignbit_b32 v10, v10, v18, v2
	ds_read_b128 v[78:81], v5
	ds_read_b128 v[70:73], v5 offset:64
	ds_read2_b32 v[18:19], v183 offset1:1
	v_add_u32_e32 v20, 0xcd4, v141
	v_add_u32_e32 v21, 0xcdc, v141
	ds_read2_b32 v[24:25], v184 offset1:1
	ds_read2_b32 v[26:27], v20 offset1:1
	ds_read2_b32 v[28:29], v21 offset1:1
	v_alignbit_b32 v16, v16, v14, v2
	s_waitcnt lgkmcnt(0)
	v_alignbit_b32 v19, v19, v18, v3
	v_alignbit_b32 v18, v18, v17, v4
	v_alignbit_b32 v17, v17, v15, v1
	v_mfma_f32_16x16x32_bf16 v[10:13], v[10:13], v[78:81], 0
	v_alignbit_b32 v15, v27, v25, v1
	v_alignbit_b32 v14, v26, v24, v2
	ds_read_b128 v[54:57], v5 offset:128
	v_mfma_f32_16x16x32_bf16 v[20:23], v[16:19], v[78:81], 0
	v_add_u32_e32 v30, 0xd1c, v141
	v_add_u32_e32 v98, 0xedc, v141
	v_add_u32_e32 v130, 0xfdc, v141
	v_mfma_f32_16x16x32_bf16 v[10:13], v[16:19], v[70:73], v[10:13]
	v_alignbit_b32 v17, v29, v28, v3
	v_alignbit_b32 v16, v28, v27, v4
	v_add_u32_e32 v28, 0xd14, v141
	s_mov_b32 s2, -16
	v_mfma_f32_16x16x32_bf16 v[18:21], v[14:17], v[70:73], v[20:23]
	s_nop 2
	v_add_u32_e32 v22, 0xd10, v141
	ds_read2_b32 v[22:23], v22 offset1:1
	ds_read2_b32 v[28:29], v28 offset1:1
	ds_read2_b32 v[30:31], v30 offset1:1
	ds_read_b128 v[58:61], v5 offset:192
	v_mfma_f32_16x16x32_bf16 v[24:27], v[14:17], v[78:81], 0
	s_waitcnt lgkmcnt(0)
	v_mfma_f32_16x16x32_bf16 v[10:13], v[14:17], v[54:57], v[10:13]
	v_add_u32_e32 v14, 0xd50, v141
	ds_read2_b32 v[32:33], v14 offset1:1
	v_alignbit_b32 v17, v31, v30, v3
	v_alignbit_b32 v16, v30, v29, v4
	v_alignbit_b32 v15, v29, v23, v1
	v_alignbit_b32 v14, v28, v22, v2
	s_nop 1
	v_mfma_f32_16x16x32_bf16 v[28:31], v[14:17], v[78:81], 0
	v_mfma_f32_16x16x32_bf16 v[22:25], v[14:17], v[70:73], v[24:27]
	v_mfma_f32_16x16x32_bf16 v[18:21], v[14:17], v[54:57], v[18:21]
	s_nop 1
	v_add_u32_e32 v26, 0xd90, v141
	v_add_u32_e32 v27, 0xd94, v141
	v_mfma_f32_16x16x32_bf16 v[10:13], v[14:17], v[58:61], v[10:13]
	v_add_u32_e32 v14, 0xd54, v141
	v_add_u32_e32 v16, 0xd5c, v141
	ds_read2_b32 v[14:15], v14 offset1:1
	ds_read2_b32 v[16:17], v16 offset1:1
	ds_read2_b32 v[36:37], v26 offset1:1
	ds_read2_b32 v[38:39], v27 offset1:1
	ds_read_b128 v[46:49], v5 offset:256
	ds_read_b128 v[42:45], v5 offset:320
	s_waitcnt lgkmcnt(0)
	v_alignbit_b32 v14, v14, v32, v2
	v_alignbit_b32 v17, v17, v16, v3
	v_alignbit_b32 v16, v16, v15, v4
	v_alignbit_b32 v15, v15, v33, v1
	s_nop 1
	v_mfma_f32_16x16x32_bf16 v[32:35], v[14:17], v[78:81], 0
	v_mfma_f32_16x16x32_bf16 v[26:29], v[14:17], v[70:73], v[28:31]
	v_mfma_f32_16x16x32_bf16 v[22:25], v[14:17], v[54:57], v[22:25]
	s_nop 1
	v_add_u32_e32 v30, 0xddc, v141
	v_mfma_f32_16x16x32_bf16 v[18:21], v[14:17], v[58:61], v[18:21]
	v_mfma_f32_16x16x32_bf16 v[10:13], v[14:17], v[46:49], v[10:13]
	v_add_u32_e32 v14, 0xd9c, v141
	ds_read2_b32 v[14:15], v14 offset1:1
	v_add_u32_e32 v16, 0xdd0, v141
	v_add_u32_e32 v17, 0xdd4, v141
	ds_read2_b32 v[40:41], v16 offset1:1
	ds_read2_b32 v[50:51], v17 offset1:1
	ds_read2_b32 v[52:53], v30 offset1:1
	s_waitcnt lgkmcnt(0)
	v_alignbit_b32 v17, v15, v14, v3
	v_alignbit_b32 v16, v14, v39, v4
	v_alignbit_b32 v15, v39, v37, v1
	v_alignbit_b32 v14, v38, v36, v2
	s_nop 1
	v_mfma_f32_16x16x32_bf16 v[36:39], v[14:17], v[78:81], 0
	v_mfma_f32_16x16x32_bf16 v[30:33], v[14:17], v[70:73], v[32:35]
	v_mfma_f32_16x16x32_bf16 v[26:29], v[14:17], v[54:57], v[26:29]
	v_mfma_f32_16x16x32_bf16 v[22:25], v[14:17], v[58:61], v[22:25]
	v_mfma_f32_16x16x32_bf16 v[18:21], v[14:17], v[46:49], v[18:21]
	v_mfma_f32_16x16x32_bf16 v[10:13], v[14:17], v[42:45], v[10:13]
	v_alignbit_b32 v17, v53, v52, v3
	v_alignbit_b32 v16, v52, v51, v4
	v_alignbit_b32 v15, v51, v41, v1
	v_alignbit_b32 v14, v50, v40, v2
	v_add_u32_e32 v40, 0xe1c, v141
	s_nop 0
	v_mfma_f32_16x16x32_bf16 v[62:65], v[14:17], v[58:61], v[26:29]
	s_nop 2
	ds_read_b128 v[26:29], v5 offset:384
	v_mfma_f32_16x16x32_bf16 v[34:37], v[14:17], v[70:73], v[36:39]
	s_nop 2
	v_add_u32_e32 v38, 0xe10, v141
	v_add_u32_e32 v39, 0xe14, v141
	ds_read2_b32 v[66:67], v38 offset1:1
	ds_read2_b32 v[68:69], v39 offset1:1
	ds_read2_b32 v[74:75], v40 offset1:1
	ds_read_b128 v[38:41], v5 offset:448
	v_mfma_f32_16x16x32_bf16 v[50:53], v[14:17], v[78:81], 0
	v_mfma_f32_16x16x32_bf16 v[30:33], v[14:17], v[54:57], v[30:33]
	v_mfma_f32_16x16x32_bf16 v[22:25], v[14:17], v[46:49], v[22:25]
	v_mfma_f32_16x16x32_bf16 v[18:21], v[14:17], v[42:45], v[18:21]
	s_waitcnt lgkmcnt(0)
	v_mfma_f32_16x16x32_bf16 v[10:13], v[14:17], v[26:29], v[10:13]
	v_add_u32_e32 v14, 0xe50, v141
	ds_read2_b32 v[76:77], v14 offset1:1
	v_alignbit_b32 v17, v75, v74, v3
	v_alignbit_b32 v16, v74, v69, v4
	v_alignbit_b32 v15, v69, v67, v1
	v_alignbit_b32 v14, v68, v66, v2
	v_add_u32_e32 v74, 0xe90, v141
	v_add_u32_e32 v75, 0xe94, v141
	v_mfma_f32_16x16x32_bf16 v[66:69], v[14:17], v[78:81], 0
	v_mfma_f32_16x16x32_bf16 v[50:53], v[14:17], v[70:73], v[50:53]
	v_mfma_f32_16x16x32_bf16 v[34:37], v[14:17], v[54:57], v[34:37]
	v_mfma_f32_16x16x32_bf16 v[30:33], v[14:17], v[58:61], v[30:33]
	v_mfma_f32_16x16x32_bf16 v[62:65], v[14:17], v[46:49], v[62:65]
	v_mfma_f32_16x16x32_bf16 v[22:25], v[14:17], v[42:45], v[22:25]
	v_mfma_f32_16x16x32_bf16 v[18:21], v[14:17], v[26:29], v[18:21]
	v_mfma_f32_16x16x32_bf16 v[10:13], v[14:17], v[38:41], v[10:13]
	v_add_u32_e32 v14, 0xe54, v141
	v_add_u32_e32 v16, 0xe5c, v141
	ds_read2_b32 v[14:15], v14 offset1:1
	ds_read2_b32 v[16:17], v16 offset1:1
	ds_read2_b32 v[90:91], v74 offset1:1
	ds_read2_b32 v[92:93], v75 offset1:1
	s_waitcnt lgkmcnt(0)
	v_alignbit_b32 v14, v14, v76, v2
	v_alignbit_b32 v17, v17, v16, v3
	v_alignbit_b32 v16, v16, v15, v4
	v_alignbit_b32 v15, v15, v77, v1
	s_nop 1
	v_mfma_f32_16x16x32_bf16 v[82:85], v[14:17], v[58:61], v[34:37]
	v_mfma_f32_16x16x32_bf16 v[86:89], v[14:17], v[46:49], v[30:33]
	s_nop 2
	ds_read_b128 v[30:33], v5 offset:512
	ds_read_b128 v[34:37], v5 offset:576
	v_mfma_f32_16x16x32_bf16 v[74:77], v[14:17], v[78:81], 0
	v_mfma_f32_16x16x32_bf16 v[66:69], v[14:17], v[70:73], v[66:69]
	v_mfma_f32_16x16x32_bf16 v[50:53], v[14:17], v[54:57], v[50:53]
	v_mfma_f32_16x16x32_bf16 v[62:65], v[14:17], v[42:45], v[62:65]
	v_mfma_f32_16x16x32_bf16 v[22:25], v[14:17], v[26:29], v[22:25]
	v_mfma_f32_16x16x32_bf16 v[18:21], v[14:17], v[38:41], v[18:21]
	s_waitcnt lgkmcnt(0)
	v_mfma_f32_16x16x32_bf16 v[10:13], v[14:17], v[30:33], v[10:13]
	v_add_u32_e32 v14, 0xe9c, v141
	ds_read2_b32 v[14:15], v14 offset1:1
	v_add_u32_e32 v16, 0xed0, v141
	v_add_u32_e32 v17, 0xed4, v141
	ds_read2_b32 v[94:95], v16 offset1:1
	ds_read2_b32 v[96:97], v17 offset1:1
	ds_read2_b32 v[98:99], v98 offset1:1
	s_waitcnt lgkmcnt(0)
	v_alignbit_b32 v17, v15, v14, v3
	v_alignbit_b32 v16, v14, v93, v4
	v_alignbit_b32 v15, v93, v91, v1
	v_alignbit_b32 v14, v92, v90, v2
	s_nop 1
	v_mfma_f32_16x16x32_bf16 v[90:93], v[14:17], v[78:81], 0
	v_mfma_f32_16x16x32_bf16 v[74:77], v[14:17], v[70:73], v[74:77]
	v_mfma_f32_16x16x32_bf16 v[66:69], v[14:17], v[54:57], v[66:69]
	v_mfma_f32_16x16x32_bf16 v[50:53], v[14:17], v[58:61], v[50:53]
	v_mfma_f32_16x16x32_bf16 v[82:85], v[14:17], v[46:49], v[82:85]
	v_mfma_f32_16x16x32_bf16 v[86:89], v[14:17], v[42:45], v[86:89]
	v_mfma_f32_16x16x32_bf16 v[62:65], v[14:17], v[26:29], v[62:65]
	v_mfma_f32_16x16x32_bf16 v[22:25], v[14:17], v[38:41], v[22:25]
	v_mfma_f32_16x16x32_bf16 v[18:21], v[14:17], v[30:33], v[18:21]
	v_mfma_f32_16x16x32_bf16 v[10:13], v[14:17], v[34:37], v[10:13]
	v_alignbit_b32 v17, v99, v98, v3
	v_alignbit_b32 v16, v98, v97, v4
	v_alignbit_b32 v15, v97, v95, v1
	v_alignbit_b32 v14, v96, v94, v2
	s_nop 1
	v_mfma_f32_16x16x32_bf16 v[98:101], v[14:17], v[30:33], v[22:25]
	s_nop 2
	ds_read_b128 v[22:25], v5 offset:640
	v_mfma_f32_16x16x32_bf16 v[102:105], v[14:17], v[34:37], v[18:21]
	s_nop 2
	v_add_u32_e32 v18, 0xf10, v141
	v_add_u32_e32 v19, 0xf14, v141
	v_add_u32_e32 v20, 0xf1c, v141
	ds_read2_b32 v[106:107], v18 offset1:1
	ds_read2_b32 v[108:109], v19 offset1:1
	ds_read2_b32 v[110:111], v20 offset1:1
	ds_read_b128 v[18:21], v5 offset:704
	v_mfma_f32_16x16x32_bf16 v[94:97], v[14:17], v[78:81], 0
	v_mfma_f32_16x16x32_bf16 v[90:93], v[14:17], v[70:73], v[90:93]
	v_mfma_f32_16x16x32_bf16 v[74:77], v[14:17], v[54:57], v[74:77]
	v_mfma_f32_16x16x32_bf16 v[66:69], v[14:17], v[58:61], v[66:69]
	v_mfma_f32_16x16x32_bf16 v[50:53], v[14:17], v[46:49], v[50:53]
	v_mfma_f32_16x16x32_bf16 v[82:85], v[14:17], v[42:45], v[82:85]
	v_mfma_f32_16x16x32_bf16 v[86:89], v[14:17], v[26:29], v[86:89]
	v_mfma_f32_16x16x32_bf16 v[62:65], v[14:17], v[38:41], v[62:65]
	s_waitcnt lgkmcnt(0)
	v_mfma_f32_16x16x32_bf16 v[10:13], v[14:17], v[22:25], v[10:13]
	v_add_u32_e32 v14, 0xf50, v141
	ds_read2_b32 v[114:115], v14 offset1:1
	v_alignbit_b32 v17, v111, v110, v3
	v_alignbit_b32 v16, v110, v109, v4
	v_alignbit_b32 v15, v109, v107, v1
	v_alignbit_b32 v14, v108, v106, v2
	s_nop 1
	v_mfma_f32_16x16x32_bf16 v[110:113], v[14:17], v[18:21], v[10:13]
	s_nop 2
	v_add_u32_e32 v10, 0xf54, v141
	v_add_u32_e32 v12, 0xf5c, v141
	ds_read2_b32 v[10:11], v10 offset1:1
	ds_read2_b32 v[12:13], v12 offset1:1
	v_mfma_f32_16x16x32_bf16 v[106:109], v[14:17], v[78:81], 0
	s_waitcnt lgkmcnt(0)
	v_alignbit_b32 v115, v11, v115, v1
	v_mfma_f32_16x16x32_bf16 v[94:97], v[14:17], v[70:73], v[94:97]
	v_alignbit_b32 v117, v13, v12, v3
	v_alignbit_b32 v116, v12, v11, v4
	v_alignbit_b32 v114, v10, v114, v2
	v_mfma_f32_16x16x32_bf16 v[90:93], v[14:17], v[54:57], v[90:93]
	v_mfma_f32_16x16x32_bf16 v[74:77], v[14:17], v[58:61], v[74:77]
	v_mfma_f32_16x16x32_bf16 v[66:69], v[14:17], v[46:49], v[66:69]
	v_mfma_f32_16x16x32_bf16 v[50:53], v[14:17], v[42:45], v[50:53]
	v_mfma_f32_16x16x32_bf16 v[82:85], v[14:17], v[26:29], v[82:85]
	v_mfma_f32_16x16x32_bf16 v[86:89], v[14:17], v[38:41], v[86:89]
	v_mfma_f32_16x16x32_bf16 v[62:65], v[14:17], v[30:33], v[62:65]
	v_mfma_f32_16x16x32_bf16 v[98:101], v[14:17], v[34:37], v[98:101]
	v_mfma_f32_16x16x32_bf16 v[102:105], v[14:17], v[22:25], v[102:105]
	v_add_u32_e32 v14, 0xf90, v141
	v_add_u32_e32 v15, 0xf94, v141
	ds_read2_b32 v[122:123], v14 offset1:1
	ds_read2_b32 v[124:125], v15 offset1:1
	ds_read_b128 v[14:17], v5 offset:768
	ds_read_b128 v[10:13], v5 offset:832
	v_mfma_f32_16x16x32_bf16 v[118:121], v[114:117], v[78:81], 0
	v_mfma_f32_16x16x32_bf16 v[106:109], v[114:117], v[70:73], v[106:109]
	v_mfma_f32_16x16x32_bf16 v[94:97], v[114:117], v[54:57], v[94:97]
	v_mfma_f32_16x16x32_bf16 v[90:93], v[114:117], v[58:61], v[90:93]
	v_mfma_f32_16x16x32_bf16 v[74:77], v[114:117], v[46:49], v[74:77]
	v_mfma_f32_16x16x32_bf16 v[66:69], v[114:117], v[42:45], v[66:69]
	v_mfma_f32_16x16x32_bf16 v[50:53], v[114:117], v[26:29], v[50:53]
	v_mfma_f32_16x16x32_bf16 v[82:85], v[114:117], v[38:41], v[82:85]
	v_mfma_f32_16x16x32_bf16 v[86:89], v[114:117], v[30:33], v[86:89]
	v_mfma_f32_16x16x32_bf16 v[62:65], v[114:117], v[34:37], v[62:65]
	v_mfma_f32_16x16x32_bf16 v[98:101], v[114:117], v[22:25], v[98:101]
	v_mfma_f32_16x16x32_bf16 v[102:105], v[114:117], v[18:21], v[102:105]
	s_waitcnt lgkmcnt(0)
	v_mfma_f32_16x16x32_bf16 v[110:113], v[114:117], v[14:17], v[110:113]
	v_add_u32_e32 v114, 0xf9c, v141
	ds_read2_b32 v[114:115], v114 offset1:1
	v_add_u32_e32 v116, 0xfd0, v141
	v_add_u32_e32 v117, 0xfd4, v141
	ds_read2_b32 v[126:127], v116 offset1:1
	ds_read2_b32 v[128:129], v117 offset1:1
	ds_read2_b32 v[166:167], v130 offset1:1
	s_waitcnt lgkmcnt(0)
	v_alignbit_b32 v117, v115, v114, v3
	v_alignbit_b32 v116, v114, v125, v4
	v_alignbit_b32 v115, v125, v123, v1
	v_alignbit_b32 v114, v124, v122, v2
	v_alignbit_b32 v169, v167, v166, v3
	v_alignbit_b32 v168, v166, v129, v4
	v_alignbit_b32 v167, v129, v127, v1
	v_alignbit_b32 v166, v128, v126, v2
	v_mfma_f32_16x16x32_bf16 v[122:125], v[114:117], v[78:81], 0
	v_mfma_f32_16x16x32_bf16 v[118:121], v[114:117], v[70:73], v[118:121]
	v_mfma_f32_16x16x32_bf16 v[106:109], v[114:117], v[54:57], v[106:109]
	v_mfma_f32_16x16x32_bf16 v[94:97], v[114:117], v[58:61], v[94:97]
	v_mfma_f32_16x16x32_bf16 v[90:93], v[114:117], v[46:49], v[90:93]
	v_mfma_f32_16x16x32_bf16 v[74:77], v[114:117], v[42:45], v[74:77]
	v_mfma_f32_16x16x32_bf16 v[66:69], v[114:117], v[26:29], v[66:69]
	v_mfma_f32_16x16x32_bf16 v[50:53], v[114:117], v[38:41], v[50:53]
	v_mfma_f32_16x16x32_bf16 v[82:85], v[114:117], v[30:33], v[82:85]
	v_mfma_f32_16x16x32_bf16 v[86:89], v[114:117], v[34:37], v[86:89]
	v_mfma_f32_16x16x32_bf16 v[62:65], v[114:117], v[22:25], v[62:65]
	v_mfma_f32_16x16x32_bf16 v[130:133], v[114:117], v[18:21], v[98:101]
	v_mfma_f32_16x16x32_bf16 v[134:137], v[114:117], v[14:17], v[102:105]
	v_mfma_f32_16x16x32_bf16 v[162:165], v[114:117], v[10:13], v[110:113]
	v_mfma_f32_16x16x32_bf16 v[126:129], v[166:169], v[78:81], 0
	v_mfma_f32_16x16x32_bf16 v[122:125], v[166:169], v[70:73], v[122:125]
	v_mfma_f32_16x16x32_bf16 v[118:121], v[166:169], v[54:57], v[118:121]
	v_mfma_f32_16x16x32_bf16 v[114:117], v[166:169], v[58:61], v[106:109]
	v_mfma_f32_16x16x32_bf16 v[110:113], v[166:169], v[46:49], v[94:97]
	v_mfma_f32_16x16x32_bf16 v[106:109], v[166:169], v[42:45], v[90:93]
	v_mfma_f32_16x16x32_bf16 v[102:105], v[166:169], v[26:29], v[74:77]
	v_mfma_f32_16x16x32_bf16 v[98:101], v[166:169], v[38:41], v[66:69]
	v_mfma_f32_16x16x32_bf16 v[94:97], v[166:169], v[30:33], v[50:53]
	v_mfma_f32_16x16x32_bf16 v[90:93], v[166:169], v[34:37], v[82:85]
	v_mfma_f32_16x16x32_bf16 v[82:85], v[166:169], v[22:25], v[86:89]
	v_mfma_f32_16x16x32_bf16 v[74:77], v[166:169], v[18:21], v[62:65]
	s_nop 1
	v_mov_b32_e32 v86, v175
	v_mov_b32_e32 v87, v174
	v_mfma_f32_16x16x32_bf16 v[66:69], v[166:169], v[14:17], v[130:133]
	v_mfma_f32_16x16x32_bf16 v[50:53], v[166:169], v[10:13], v[134:137]
	s_nop 1
	v_mov_b32_e32 v130, 0
	v_mov_b32_e32 v131, v130
	v_mov_b32_e32 v132, v130
	v_mfma_f32_16x16x32_bf16 v[62:65], v[166:169], v[6:9], v[162:165]
	v_mov_b32_e32 v133, v130

.LBB0_2209:
	s_add_i32 s20, s12, 0x400
	s_ashr_i32 s20, s20, 3
	s_ashr_i32 s21, s20, 31
	s_lshl_b64 s[20:21], s[20:21], 7
	s_and_b32 s32, s12, 7
	v_mov_b32_e32 v244, s32
	v_or3_b32 v244, s20, v140, v244
	v_mov_b32_e32 v245, s21
	v_lshlrev_b64 v[244:245], 12, v[244:245]
	v_lshl_add_u64 v[244:245], v[160:161], 0, v[244:245]
	global_load_dword v233, v[244:245], off
	global_load_dword v233, v[244:245], off offset:64
	global_load_dword v233, v[244:245], off offset:128
	global_load_dword v233, v[244:245], off offset:192
	global_load_dword v233, v[244:245], off offset:256
	global_load_dword v233, v[244:245], off offset:320
	global_load_dword v233, v[244:245], off offset:384
	global_load_dword v233, v[244:245], off offset:448
	global_load_dword v233, v[244:245], off offset:512
	global_load_dword v233, v[244:245], off offset:576
	global_load_dword v233, v[244:245], off offset:640
	global_load_dword v233, v[244:245], off offset:704
	global_load_dword v233, v[244:245], off offset:768
	global_load_dword v233, v[244:245], off offset:832
	global_load_dword v233, v[244:245], off offset:896
	global_load_dword v233, v[244:245], off offset:960
	v_add_u32_e32 v6, 0xc50, v173
	ds_read2_b32 v[10:11], v6 offset1:1
	v_add_u32_e32 v6, 0xc54, v173
	v_add_u32_e32 v7, 0xc5c, v173
	ds_read2_b32 v[14:15], v6 offset1:1
	ds_read2_b32 v[6:7], v7 offset1:1
	v_add_u32_e32 v8, 0xc90, v173
	v_add_u32_e32 v9, 0xc94, v173
	ds_read2_b32 v[16:17], v8 offset1:1
	ds_read2_b32 v[18:19], v9 offset1:1
	s_waitcnt lgkmcnt(0)
	v_alignbit_b32 v10, v14, v10, v2
	v_add_u32_e32 v14, 0xc9c, v173
	v_alignbit_b32 v13, v7, v6, v3
	v_alignbit_b32 v12, v6, v15, v4
	ds_read_b128 v[6:9], v171 offset:896
	v_alignbit_b32 v11, v15, v11, v1
	ds_read_b128 v[74:77], v171
	ds_read_b128 v[66:69], v171 offset:64
	ds_read2_b32 v[14:15], v14 offset1:1
	v_add_u32_e32 v20, 0xcd0, v173
	v_add_u32_e32 v21, 0xcd4, v173
	v_add_u32_e32 v26, 0xcdc, v173
	ds_read2_b32 v[22:23], v20 offset1:1
	ds_read2_b32 v[24:25], v21 offset1:1
	ds_read2_b32 v[26:27], v26 offset1:1
	s_waitcnt lgkmcnt(0)
	v_alignbit_b32 v21, v15, v14, v3
	v_alignbit_b32 v20, v14, v19, v4
	v_alignbit_b32 v19, v19, v17, v1
	v_alignbit_b32 v18, v18, v16, v2
	v_mfma_f32_16x16x32_bf16 v[10:13], v[10:13], v[74:77], 0
	ds_read_b128 v[50:53], v171 offset:128
	v_add_u32_e32 v28, 0xd14, v173
	v_add_u32_e32 v30, 0xd1c, v173
	v_mfma_f32_16x16x32_bf16 v[14:17], v[18:21], v[74:77], 0
	v_add_u32_e32 v54, 0xddc, v173
	v_add_u32_e32 v96, 0xedc, v173
	v_add_u32_e32 v130, 0xfdc, v173
	v_mfma_f32_16x16x32_bf16 v[10:13], v[18:21], v[66:69], v[10:13]
	v_alignbit_b32 v21, v27, v26, v3
	v_alignbit_b32 v20, v26, v25, v4
	v_alignbit_b32 v19, v25, v23, v1
	v_alignbit_b32 v18, v24, v22, v2
	v_add_u32_e32 v26, 0xd10, v173
	ds_read2_b32 v[26:27], v26 offset1:1
	ds_read2_b32 v[28:29], v28 offset1:1
	ds_read2_b32 v[30:31], v30 offset1:1
	ds_read_b128 v[58:61], v171 offset:192
	v_mfma_f32_16x16x32_bf16 v[22:25], v[18:21], v[74:77], 0
	s_mov_b32 s2, -16
	v_mfma_f32_16x16x32_bf16 v[14:17], v[18:21], v[66:69], v[14:17]
	s_waitcnt lgkmcnt(0)
	v_mfma_f32_16x16x32_bf16 v[10:13], v[18:21], v[50:53], v[10:13]
	v_add_u32_e32 v18, 0xd50, v173
	ds_read2_b32 v[32:33], v18 offset1:1
	v_alignbit_b32 v21, v31, v30, v3
	v_alignbit_b32 v20, v30, v29, v4
	v_alignbit_b32 v19, v29, v27, v1
	v_alignbit_b32 v18, v28, v26, v2
	v_add_u32_e32 v30, 0xd90, v173
	v_add_u32_e32 v31, 0xd94, v173
	v_mfma_f32_16x16x32_bf16 v[26:29], v[18:21], v[74:77], 0
	v_mfma_f32_16x16x32_bf16 v[22:25], v[18:21], v[66:69], v[22:25]
	v_mfma_f32_16x16x32_bf16 v[14:17], v[18:21], v[50:53], v[14:17]
	v_mfma_f32_16x16x32_bf16 v[10:13], v[18:21], v[58:61], v[10:13]
	v_add_u32_e32 v18, 0xd54, v173
	v_add_u32_e32 v20, 0xd5c, v173
	ds_read2_b32 v[18:19], v18 offset1:1
	ds_read2_b32 v[20:21], v20 offset1:1
	ds_read2_b32 v[34:35], v30 offset1:1
	ds_read2_b32 v[36:37], v31 offset1:1
	ds_read_b128 v[46:49], v171 offset:256
	ds_read_b128 v[42:45], v171 offset:320
	s_waitcnt lgkmcnt(0)
	v_alignbit_b32 v18, v18, v32, v2
	v_alignbit_b32 v21, v21, v20, v3
	v_alignbit_b32 v20, v20, v19, v4
	v_alignbit_b32 v19, v19, v33, v1
	s_nop 1
	v_mfma_f32_16x16x32_bf16 v[30:33], v[18:21], v[74:77], 0
	v_mfma_f32_16x16x32_bf16 v[26:29], v[18:21], v[66:69], v[26:29]
	v_mfma_f32_16x16x32_bf16 v[22:25], v[18:21], v[50:53], v[22:25]
	v_mfma_f32_16x16x32_bf16 v[14:17], v[18:21], v[58:61], v[14:17]
	v_mfma_f32_16x16x32_bf16 v[10:13], v[18:21], v[46:49], v[10:13]
	v_add_u32_e32 v18, 0xd9c, v173
	ds_read2_b32 v[18:19], v18 offset1:1
	v_add_u32_e32 v20, 0xdd0, v173
	v_add_u32_e32 v21, 0xdd4, v173
	ds_read2_b32 v[38:39], v20 offset1:1
	ds_read2_b32 v[40:41], v21 offset1:1
	ds_read2_b32 v[54:55], v54 offset1:1
	s_waitcnt lgkmcnt(0)
	v_alignbit_b32 v21, v19, v18, v3
	v_alignbit_b32 v20, v18, v37, v4
	v_alignbit_b32 v19, v37, v35, v1
	v_alignbit_b32 v18, v36, v34, v2
	s_nop 1
	v_mfma_f32_16x16x32_bf16 v[34:37], v[18:21], v[74:77], 0
	v_mfma_f32_16x16x32_bf16 v[30:33], v[18:21], v[66:69], v[30:33]
	v_mfma_f32_16x16x32_bf16 v[26:29], v[18:21], v[50:53], v[26:29]
	v_mfma_f32_16x16x32_bf16 v[22:25], v[18:21], v[58:61], v[22:25]
	v_mfma_f32_16x16x32_bf16 v[14:17], v[18:21], v[46:49], v[14:17]
	v_mfma_f32_16x16x32_bf16 v[10:13], v[18:21], v[42:45], v[10:13]
	v_alignbit_b32 v21, v55, v54, v3
	v_alignbit_b32 v20, v54, v41, v4
	v_alignbit_b32 v19, v41, v39, v1
	v_alignbit_b32 v18, v40, v38, v2
	v_add_u32_e32 v38, 0xe10, v173
	v_add_u32_e32 v39, 0xe14, v173
	v_mfma_f32_16x16x32_bf16 v[62:65], v[18:21], v[46:49], v[22:25]
	v_add_u32_e32 v40, 0xe1c, v173
	s_nop 1
	ds_read_b128 v[22:25], v171 offset:384
	ds_read2_b32 v[70:71], v38 offset1:1
	ds_read2_b32 v[72:73], v39 offset1:1
	ds_read2_b32 v[78:79], v40 offset1:1
	ds_read_b128 v[38:41], v171 offset:448
	v_mfma_f32_16x16x32_bf16 v[54:57], v[18:21], v[74:77], 0
	v_mfma_f32_16x16x32_bf16 v[34:37], v[18:21], v[66:69], v[34:37]
	v_mfma_f32_16x16x32_bf16 v[30:33], v[18:21], v[50:53], v[30:33]
	v_mfma_f32_16x16x32_bf16 v[26:29], v[18:21], v[58:61], v[26:29]
	v_mfma_f32_16x16x32_bf16 v[14:17], v[18:21], v[42:45], v[14:17]
	s_waitcnt lgkmcnt(0)
	v_mfma_f32_16x16x32_bf16 v[10:13], v[18:21], v[22:25], v[10:13]
	v_add_u32_e32 v18, 0xe50, v173
	ds_read2_b32 v[80:81], v18 offset1:1
	v_alignbit_b32 v21, v79, v78, v3
	v_alignbit_b32 v20, v78, v73, v4
	v_alignbit_b32 v19, v73, v71, v1
	v_alignbit_b32 v18, v72, v70, v2
	v_add_u32_e32 v78, 0xe90, v173
	v_add_u32_e32 v79, 0xe94, v173
	v_mfma_f32_16x16x32_bf16 v[70:73], v[18:21], v[74:77], 0
	v_mfma_f32_16x16x32_bf16 v[54:57], v[18:21], v[66:69], v[54:57]
	v_mfma_f32_16x16x32_bf16 v[34:37], v[18:21], v[50:53], v[34:37]
	v_mfma_f32_16x16x32_bf16 v[30:33], v[18:21], v[58:61], v[30:33]
	v_mfma_f32_16x16x32_bf16 v[26:29], v[18:21], v[46:49], v[26:29]
	v_mfma_f32_16x16x32_bf16 v[62:65], v[18:21], v[42:45], v[62:65]
	v_mfma_f32_16x16x32_bf16 v[14:17], v[18:21], v[22:25], v[14:17]
	v_mfma_f32_16x16x32_bf16 v[10:13], v[18:21], v[38:41], v[10:13]
	v_add_u32_e32 v18, 0xe54, v173
	v_add_u32_e32 v20, 0xe5c, v173
	ds_read2_b32 v[18:19], v18 offset1:1
	ds_read2_b32 v[20:21], v20 offset1:1
	ds_read2_b32 v[90:91], v78 offset1:1
	ds_read2_b32 v[92:93], v79 offset1:1
	s_waitcnt lgkmcnt(0)
	v_alignbit_b32 v18, v18, v80, v2
	v_alignbit_b32 v21, v21, v20, v3
	v_alignbit_b32 v20, v20, v19, v4
	v_alignbit_b32 v19, v19, v81, v1
	s_nop 1
	v_mfma_f32_16x16x32_bf16 v[82:85], v[18:21], v[58:61], v[34:37]
	v_mfma_f32_16x16x32_bf16 v[86:89], v[18:21], v[46:49], v[30:33]
	s_nop 2
	ds_read_b128 v[30:33], v171 offset:512
	ds_read_b128 v[34:37], v171 offset:576
	v_mfma_f32_16x16x32_bf16 v[78:81], v[18:21], v[74:77], 0
	v_mfma_f32_16x16x32_bf16 v[70:73], v[18:21], v[66:69], v[70:73]
	v_mfma_f32_16x16x32_bf16 v[54:57], v[18:21], v[50:53], v[54:57]
	v_mfma_f32_16x16x32_bf16 v[26:29], v[18:21], v[42:45], v[26:29]
	v_mfma_f32_16x16x32_bf16 v[62:65], v[18:21], v[22:25], v[62:65]
	v_mfma_f32_16x16x32_bf16 v[14:17], v[18:21], v[38:41], v[14:17]
	s_waitcnt lgkmcnt(0)
	v_mfma_f32_16x16x32_bf16 v[10:13], v[18:21], v[30:33], v[10:13]
	v_add_u32_e32 v18, 0xe9c, v173
	ds_read2_b32 v[18:19], v18 offset1:1
	v_add_u32_e32 v20, 0xed0, v173
	v_add_u32_e32 v21, 0xed4, v173
	ds_read2_b32 v[94:95], v20 offset1:1
	ds_read2_b32 v[98:99], v21 offset1:1
	ds_read2_b32 v[96:97], v96 offset1:1
	s_waitcnt lgkmcnt(0)
	v_alignbit_b32 v21, v19, v18, v3
	v_alignbit_b32 v20, v18, v93, v4
	v_alignbit_b32 v19, v93, v91, v1
	v_alignbit_b32 v18, v92, v90, v2
	v_alignbit_b32 v97, v97, v96, v3
	v_alignbit_b32 v96, v96, v99, v4
	v_alignbit_b32 v95, v99, v95, v1
	v_alignbit_b32 v94, v98, v94, v2
	v_mfma_f32_16x16x32_bf16 v[26:29], v[18:21], v[22:25], v[26:29]
	s_nop 0
	v_mfma_f32_16x16x32_bf16 v[102:105], v[94:97], v[38:41], v[26:29]
	v_mfma_f32_16x16x32_bf16 v[90:93], v[18:21], v[74:77], 0
	s_nop 4
	ds_read_b128 v[26:29], v171 offset:640
	v_mfma_f32_16x16x32_bf16 v[78:81], v[18:21], v[66:69], v[78:81]
	v_mfma_f32_16x16x32_bf16 v[70:73], v[18:21], v[50:53], v[70:73]
	v_mfma_f32_16x16x32_bf16 v[54:57], v[18:21], v[58:61], v[54:57]
	v_mfma_f32_16x16x32_bf16 v[82:85], v[18:21], v[46:49], v[82:85]
	v_mfma_f32_16x16x32_bf16 v[86:89], v[18:21], v[42:45], v[86:89]
	v_mfma_f32_16x16x32_bf16 v[62:65], v[18:21], v[38:41], v[62:65]
	v_mfma_f32_16x16x32_bf16 v[14:17], v[18:21], v[30:33], v[14:17]
	v_mfma_f32_16x16x32_bf16 v[10:13], v[18:21], v[34:37], v[10:13]
	v_add_u32_e32 v18, 0xf10, v173
	v_add_u32_e32 v19, 0xf14, v173
	v_add_u32_e32 v20, 0xf1c, v173
	ds_read2_b32 v[106:107], v18 offset1:1
	ds_read2_b32 v[108:109], v19 offset1:1
	ds_read2_b32 v[110:111], v20 offset1:1
	ds_read_b128 v[18:21], v171 offset:704
	v_mfma_f32_16x16x32_bf16 v[98:101], v[94:97], v[74:77], 0
	v_mfma_f32_16x16x32_bf16 v[90:93], v[94:97], v[66:69], v[90:93]
	v_mfma_f32_16x16x32_bf16 v[78:81], v[94:97], v[50:53], v[78:81]
	v_mfma_f32_16x16x32_bf16 v[70:73], v[94:97], v[58:61], v[70:73]
	v_mfma_f32_16x16x32_bf16 v[54:57], v[94:97], v[46:49], v[54:57]
	v_mfma_f32_16x16x32_bf16 v[82:85], v[94:97], v[42:45], v[82:85]
	v_mfma_f32_16x16x32_bf16 v[86:89], v[94:97], v[22:25], v[86:89]
	v_mfma_f32_16x16x32_bf16 v[62:65], v[94:97], v[30:33], v[62:65]
	v_mfma_f32_16x16x32_bf16 v[14:17], v[94:97], v[34:37], v[14:17]
	s_waitcnt lgkmcnt(0)
	v_mfma_f32_16x16x32_bf16 v[10:13], v[94:97], v[26:29], v[10:13]
	v_add_u32_e32 v94, 0xf50, v173
	ds_read2_b32 v[114:115], v94 offset1:1
	v_alignbit_b32 v97, v111, v110, v3
	v_alignbit_b32 v96, v110, v109, v4
	v_alignbit_b32 v95, v109, v107, v1
	v_alignbit_b32 v94, v108, v106, v2
	v_add_u32_e32 v110, 0xf90, v173
	v_add_u32_e32 v111, 0xf94, v173
	v_mfma_f32_16x16x32_bf16 v[106:109], v[94:97], v[74:77], 0
	v_mfma_f32_16x16x32_bf16 v[98:101], v[94:97], v[66:69], v[98:101]
	v_mfma_f32_16x16x32_bf16 v[90:93], v[94:97], v[50:53], v[90:93]
	v_mfma_f32_16x16x32_bf16 v[78:81], v[94:97], v[58:61], v[78:81]
	v_mfma_f32_16x16x32_bf16 v[70:73], v[94:97], v[46:49], v[70:73]
	v_mfma_f32_16x16x32_bf16 v[54:57], v[94:97], v[42:45], v[54:57]
	v_mfma_f32_16x16x32_bf16 v[82:85], v[94:97], v[22:25], v[82:85]
	v_mfma_f32_16x16x32_bf16 v[86:89], v[94:97], v[38:41], v[86:89]
	v_mfma_f32_16x16x32_bf16 v[102:105], v[94:97], v[30:33], v[102:105]
	v_mfma_f32_16x16x32_bf16 v[62:65], v[94:97], v[34:37], v[62:65]
	v_mfma_f32_16x16x32_bf16 v[14:17], v[94:97], v[26:29], v[14:17]
	v_mfma_f32_16x16x32_bf16 v[94:97], v[94:97], v[18:21], v[10:13]
	s_nop 2
	v_add_u32_e32 v10, 0xf54, v173
	v_add_u32_e32 v12, 0xf5c, v173
	ds_read2_b32 v[10:11], v10 offset1:1
	ds_read2_b32 v[12:13], v12 offset1:1
	ds_read2_b32 v[122:123], v110 offset1:1
	ds_read2_b32 v[124:125], v111 offset1:1
	s_waitcnt lgkmcnt(0)
	v_alignbit_b32 v111, v11, v115, v1
	v_alignbit_b32 v113, v13, v12, v3
	v_alignbit_b32 v112, v12, v11, v4
	v_alignbit_b32 v110, v10, v114, v2
	s_nop 1
	v_mfma_f32_16x16x32_bf16 v[118:121], v[110:113], v[18:21], v[14:17]
	s_nop 2
	ds_read_b128 v[14:17], v171 offset:768
	ds_read_b128 v[10:13], v171 offset:832
	v_mfma_f32_16x16x32_bf16 v[114:117], v[110:113], v[74:77], 0
	v_mfma_f32_16x16x32_bf16 v[106:109], v[110:113], v[66:69], v[106:109]
	v_mfma_f32_16x16x32_bf16 v[98:101], v[110:113], v[50:53], v[98:101]
	v_mfma_f32_16x16x32_bf16 v[90:93], v[110:113], v[58:61], v[90:93]
	v_mfma_f32_16x16x32_bf16 v[78:81], v[110:113], v[46:49], v[78:81]
	v_mfma_f32_16x16x32_bf16 v[70:73], v[110:113], v[42:45], v[70:73]
	v_mfma_f32_16x16x32_bf16 v[54:57], v[110:113], v[22:25], v[54:57]
	v_mfma_f32_16x16x32_bf16 v[82:85], v[110:113], v[38:41], v[82:85]
	v_mfma_f32_16x16x32_bf16 v[86:89], v[110:113], v[30:33], v[86:89]
	v_mfma_f32_16x16x32_bf16 v[102:105], v[110:113], v[34:37], v[102:105]
	v_mfma_f32_16x16x32_bf16 v[62:65], v[110:113], v[26:29], v[62:65]
	s_waitcnt lgkmcnt(0)
	v_mfma_f32_16x16x32_bf16 v[94:97], v[110:113], v[14:17], v[94:97]
	v_add_u32_e32 v110, 0xf9c, v173
	ds_read2_b32 v[110:111], v110 offset1:1
	v_add_u32_e32 v112, 0xfd0, v173
	v_add_u32_e32 v113, 0xfd4, v173
	ds_read2_b32 v[126:127], v112 offset1:1
	ds_read2_b32 v[128:129], v113 offset1:1
	ds_read2_b32 v[166:167], v130 offset1:1
	s_waitcnt lgkmcnt(0)
	v_alignbit_b32 v113, v111, v110, v3
	v_alignbit_b32 v112, v110, v125, v4
	v_alignbit_b32 v111, v125, v123, v1
	v_alignbit_b32 v110, v124, v122, v2
	v_alignbit_b32 v169, v167, v166, v3
	v_alignbit_b32 v168, v166, v129, v4
	v_alignbit_b32 v167, v129, v127, v1
	v_alignbit_b32 v166, v128, v126, v2
	v_mfma_f32_16x16x32_bf16 v[122:125], v[110:113], v[74:77], 0
	v_mfma_f32_16x16x32_bf16 v[114:117], v[110:113], v[66:69], v[114:117]
	v_mfma_f32_16x16x32_bf16 v[106:109], v[110:113], v[50:53], v[106:109]
	v_mfma_f32_16x16x32_bf16 v[98:101], v[110:113], v[58:61], v[98:101]
	v_mfma_f32_16x16x32_bf16 v[90:93], v[110:113], v[46:49], v[90:93]
	v_mfma_f32_16x16x32_bf16 v[78:81], v[110:113], v[42:45], v[78:81]
	v_mfma_f32_16x16x32_bf16 v[70:73], v[110:113], v[22:25], v[70:73]
	v_mfma_f32_16x16x32_bf16 v[54:57], v[110:113], v[38:41], v[54:57]
	v_mfma_f32_16x16x32_bf16 v[82:85], v[110:113], v[30:33], v[82:85]
	v_mfma_f32_16x16x32_bf16 v[86:89], v[110:113], v[34:37], v[86:89]
	v_mfma_f32_16x16x32_bf16 v[130:133], v[110:113], v[26:29], v[102:105]
	v_mfma_f32_16x16x32_bf16 v[62:65], v[110:113], v[18:21], v[62:65]
	v_mfma_f32_16x16x32_bf16 v[134:137], v[110:113], v[14:17], v[118:121]
	v_mfma_f32_16x16x32_bf16 v[162:165], v[110:113], v[10:13], v[94:97]
	v_mfma_f32_16x16x32_bf16 v[126:129], v[166:169], v[74:77], 0
	v_mfma_f32_16x16x32_bf16 v[122:125], v[166:169], v[66:69], v[122:125]
	v_mfma_f32_16x16x32_bf16 v[118:121], v[166:169], v[50:53], v[114:117]
	v_mfma_f32_16x16x32_bf16 v[114:117], v[166:169], v[58:61], v[106:109]
	v_mfma_f32_16x16x32_bf16 v[110:113], v[166:169], v[46:49], v[98:101]
	v_mfma_f32_16x16x32_bf16 v[106:109], v[166:169], v[42:45], v[90:93]
	v_mfma_f32_16x16x32_bf16 v[102:105], v[166:169], v[22:25], v[78:81]
	v_mfma_f32_16x16x32_bf16 v[98:101], v[166:169], v[38:41], v[70:73]
	v_mfma_f32_16x16x32_bf16 v[94:97], v[166:169], v[30:33], v[54:57]
	v_mfma_f32_16x16x32_bf16 v[90:93], v[166:169], v[34:37], v[82:85]
	v_mfma_f32_16x16x32_bf16 v[82:85], v[166:169], v[26:29], v[86:89]
	v_mfma_f32_16x16x32_bf16 v[78:81], v[166:169], v[18:21], v[130:133]
	s_nop 1
	v_mov_b32_e32 v86, v176
	v_mov_b32_e32 v87, v174
	v_mfma_f32_16x16x32_bf16 v[70:73], v[166:169], v[14:17], v[62:65]
	v_mov_b32_e32 v130, 0
	v_mov_b32_e32 v131, v130
	v_mov_b32_e32 v132, v130
	v_mfma_f32_16x16x32_bf16 v[54:57], v[166:169], v[10:13], v[134:137]
	v_mov_b32_e32 v133, v130
	v_mfma_f32_16x16x32_bf16 v[62:65], v[166:169], v[6:9], v[162:165]
.LBB0_2210:
	v_and_b32_e32 v88, 0x7ffffffe, v87
	v_add_u32_e32 v89, 32, v87
	v_lshl_add_u32 v136, v88, 1, s38
	v_and_b32_e32 v137, 0x7ffffffe, v89
	ds_read2_b32 v[88:89], v136 offset0:3 offset1:4
	ds_read2_b32 v[134:135], v136 offset0:1 offset1:2
	ds_read2_b32 v[162:163], v136 offset1:1
	v_lshl_add_u32 v168, v137, 1, s38
	ds_read2_b32 v[166:167], v168 offset1:1
	s_waitcnt lgkmcnt(0)
	v_alignbit_b32 v137, v89, v88, v3
	v_alignbit_b32 v136, v88, v135, v4
	v_alignbit_b32 v135, v135, v163, v1
	v_alignbit_b32 v134, v134, v162, v2
	s_add_i32 s2, s2, 16
	s_cmp_lt_u32 s2, 32
	v_mfma_f32_16x16x32_bf16 v[130:133], v[134:137], v[74:77], v[130:133]
	v_add_u32_e32 v74, 64, v87
	v_and_b32_e32 v74, 0x7ffffffe, v74
	v_lshl_add_u32 v190, v74, 1, s38
	v_mfma_f32_16x16x32_bf16 v[88:91], v[134:137], v[26:29], v[90:93]
	v_mfma_f32_16x16x32_bf16 v[162:165], v[134:137], v[18:21], v[82:85]
	s_nop 2
	ds_read_b128 v[82:85], v86
	ds_read2_b32 v[74:75], v168 offset0:3 offset1:4
	ds_read2_b32 v[92:93], v168 offset0:1 offset1:2
	v_mfma_f32_16x16x32_bf16 v[94:97], v[134:137], v[34:37], v[94:97]
	ds_read2_b32 v[186:187], v190 offset1:1
	ds_read2_b32 v[188:189], v190 offset0:1 offset1:2
	s_waitcnt lgkmcnt(0)
	v_alignbit_b32 v169, v75, v74, v3
	v_alignbit_b32 v168, v74, v93, v4
	v_alignbit_b32 v167, v93, v167, v1
	v_alignbit_b32 v166, v92, v166, v2
	v_mfma_f32_16x16x32_bf16 v[126:129], v[134:137], v[66:69], v[126:129]
	ds_read_b128 v[74:77], v86 offset:64
	v_mfma_f32_16x16x32_bf16 v[92:95], v[166:169], v[26:29], v[94:97]
	s_nop 2
	v_add_u32_e32 v96, 0x60, v87
	v_and_b32_e32 v96, 0x7ffffffe, v96
	v_mfma_f32_16x16x32_bf16 v[122:125], v[134:137], v[50:53], v[122:125]
	v_mfma_f32_16x16x32_bf16 v[118:121], v[134:137], v[58:61], v[118:121]
	v_mfma_f32_16x16x32_bf16 v[114:117], v[134:137], v[46:49], v[114:117]
	v_mfma_f32_16x16x32_bf16 v[110:113], v[134:137], v[42:45], v[110:113]
	v_mfma_f32_16x16x32_bf16 v[106:109], v[134:137], v[22:25], v[106:109]
	v_mfma_f32_16x16x32_bf16 v[102:105], v[134:137], v[38:41], v[102:105]
	v_mfma_f32_16x16x32_bf16 v[98:101], v[134:137], v[30:33], v[98:101]
	v_mfma_f32_16x16x32_bf16 v[78:81], v[134:137], v[14:17], v[78:81]
	v_mfma_f32_16x16x32_bf16 v[70:73], v[134:137], v[10:13], v[70:73]
	v_mfma_f32_16x16x32_bf16 v[54:57], v[134:137], v[6:9], v[54:57]
	v_mfma_f32_16x16x32_bf16 v[62:65], v[134:137], v[82:85], v[62:65]
	v_lshl_add_u32 v134, v96, 1, s38
	ds_read2_b32 v[96:97], v190 offset0:3 offset1:4
	ds_read2_b32 v[190:191], v134 offset1:1
	ds_read2_b32 v[192:193], v134 offset0:1 offset1:2
	ds_read2_b32 v[194:195], v134 offset0:3 offset1:4
	v_alignbit_b32 v135, v189, v187, v1
	v_alignbit_b32 v134, v188, v186, v2
	v_mfma_f32_16x16x32_bf16 v[102:105], v[166:169], v[30:33], v[102:105]
	s_waitcnt lgkmcnt(0)
	v_alignbit_b32 v137, v97, v96, v3
	v_alignbit_b32 v136, v96, v189, v4
	v_mfma_f32_16x16x32_bf16 v[66:69], v[166:169], v[66:69], v[130:133]
	v_mfma_f32_16x16x32_bf16 v[126:129], v[166:169], v[50:53], v[126:129]
	v_mfma_f32_16x16x32_bf16 v[122:125], v[166:169], v[58:61], v[122:125]
	v_mfma_f32_16x16x32_bf16 v[118:121], v[166:169], v[46:49], v[118:121]
	v_mfma_f32_16x16x32_bf16 v[114:117], v[166:169], v[42:45], v[114:117]
	v_mfma_f32_16x16x32_bf16 v[110:113], v[166:169], v[22:25], v[110:113]
	v_mfma_f32_16x16x32_bf16 v[106:109], v[166:169], v[38:41], v[106:109]
	v_mfma_f32_16x16x32_bf16 v[98:101], v[166:169], v[34:37], v[98:101]
	v_mfma_f32_16x16x32_bf16 v[88:91], v[166:169], v[18:21], v[88:91]
	v_mfma_f32_16x16x32_bf16 v[130:133], v[166:169], v[14:17], v[162:165]
	v_mfma_f32_16x16x32_bf16 v[78:81], v[166:169], v[10:13], v[78:81]
	v_mfma_f32_16x16x32_bf16 v[70:73], v[166:169], v[6:9], v[70:73]
	v_mfma_f32_16x16x32_bf16 v[54:57], v[166:169], v[82:85], v[54:57]
	v_mfma_f32_16x16x32_bf16 v[62:65], v[166:169], v[74:77], v[62:65]
	v_alignbit_b32 v169, v195, v194, v3
	v_alignbit_b32 v168, v194, v193, v4
	v_alignbit_b32 v167, v193, v191, v1
	v_alignbit_b32 v166, v192, v190, v2
	v_mfma_f32_16x16x32_bf16 v[102:105], v[134:137], v[34:37], v[102:105]
	v_mfma_f32_16x16x32_bf16 v[162:165], v[134:137], v[50:53], v[66:69]
	s_nop 2
	ds_read_b128 v[66:69], v86 offset:128
	ds_read_b128 v[50:53], v86 offset:192
	v_mfma_f32_16x16x32_bf16 v[96:99], v[134:137], v[26:29], v[98:101]
	v_mfma_f32_16x16x32_bf16 v[100:103], v[166:169], v[26:29], v[102:105]
	s_nop 2
	v_add_u32_e32 v104, 0x80, v87
	v_add_u32_e32 v105, 0xa0, v87
	v_and_b32_e32 v104, 0x7ffffffe, v104
	v_mfma_f32_16x16x32_bf16 v[126:129], v[134:137], v[58:61], v[126:129]
	v_and_b32_e32 v105, 0x7ffffffe, v105
	v_lshl_add_u32 v188, v105, 1, s38
	v_mfma_f32_16x16x32_bf16 v[122:125], v[134:137], v[46:49], v[122:125]
	v_mfma_f32_16x16x32_bf16 v[118:121], v[134:137], v[42:45], v[118:121]
	v_mfma_f32_16x16x32_bf16 v[114:117], v[134:137], v[22:25], v[114:117]
	v_mfma_f32_16x16x32_bf16 v[110:113], v[134:137], v[38:41], v[110:113]
	v_mfma_f32_16x16x32_bf16 v[106:109], v[134:137], v[30:33], v[106:109]
	v_mfma_f32_16x16x32_bf16 v[92:95], v[134:137], v[18:21], v[92:95]
	v_mfma_f32_16x16x32_bf16 v[88:91], v[134:137], v[14:17], v[88:91]
	v_mfma_f32_16x16x32_bf16 v[130:133], v[134:137], v[10:13], v[130:133]
	v_mfma_f32_16x16x32_bf16 v[78:81], v[134:137], v[6:9], v[78:81]
	v_mfma_f32_16x16x32_bf16 v[70:73], v[134:137], v[82:85], v[70:73]
	v_mfma_f32_16x16x32_bf16 v[54:57], v[134:137], v[74:77], v[54:57]
	s_waitcnt lgkmcnt(0)
	v_mfma_f32_16x16x32_bf16 v[62:65], v[134:137], v[66:69], v[62:65]
	v_lshl_add_u32 v136, v104, 1, s38
	ds_read2_b32 v[104:105], v136 offset0:3 offset1:4
	s_waitcnt lgkmcnt(0)
	v_alignbit_b32 v137, v105, v104, v3
	v_mfma_f32_16x16x32_bf16 v[58:61], v[166:169], v[58:61], v[162:165]
	ds_read2_b32 v[134:135], v136 offset0:1 offset1:2
	s_nop 1
	ds_read2_b32 v[162:163], v136 offset1:1
	ds_read2_b32 v[186:187], v188 offset1:1
	s_waitcnt lgkmcnt(0)
	v_alignbit_b32 v136, v104, v135, v4
	v_alignbit_b32 v135, v135, v163, v1
	v_alignbit_b32 v134, v134, v162, v2
	v_mfma_f32_16x16x32_bf16 v[126:129], v[166:169], v[46:49], v[126:129]
	v_mfma_f32_16x16x32_bf16 v[106:109], v[166:169], v[34:37], v[106:109]
	v_mfma_f32_16x16x32_bf16 v[162:165], v[134:137], v[46:49], v[58:61]
	v_add_u32_e32 v46, 0xc0, v87
	v_and_b32_e32 v46, 0x7ffffffe, v46
	v_lshl_add_u32 v192, v46, 1, s38
	ds_read2_b32 v[46:47], v188 offset0:3 offset1:4
	v_mfma_f32_16x16x32_bf16 v[110:113], v[166:169], v[30:33], v[110:113]
	v_mfma_f32_16x16x32_bf16 v[104:107], v[134:137], v[26:29], v[106:109]
	s_nop 2
	ds_read2_b32 v[108:109], v188 offset0:1 offset1:2
	ds_read2_b32 v[188:189], v192 offset1:1
	ds_read2_b32 v[190:191], v192 offset0:1 offset1:2
	v_mfma_f32_16x16x32_bf16 v[122:125], v[166:169], v[42:45], v[122:125]
	v_mfma_f32_16x16x32_bf16 v[118:121], v[166:169], v[22:25], v[118:121]
	v_mfma_f32_16x16x32_bf16 v[114:117], v[166:169], v[38:41], v[114:117]
	v_mfma_f32_16x16x32_bf16 v[96:99], v[166:169], v[18:21], v[96:99]
	v_mfma_f32_16x16x32_bf16 v[92:95], v[166:169], v[14:17], v[92:95]
	v_mfma_f32_16x16x32_bf16 v[88:91], v[166:169], v[10:13], v[88:91]
	v_mfma_f32_16x16x32_bf16 v[130:133], v[166:169], v[6:9], v[130:133]
	v_mfma_f32_16x16x32_bf16 v[78:81], v[166:169], v[82:85], v[78:81]
	v_mfma_f32_16x16x32_bf16 v[70:73], v[166:169], v[74:77], v[70:73]
	v_mfma_f32_16x16x32_bf16 v[54:57], v[166:169], v[66:69], v[54:57]
	v_mfma_f32_16x16x32_bf16 v[62:65], v[166:169], v[50:53], v[62:65]
	s_waitcnt lgkmcnt(0)
	v_alignbit_b32 v169, v47, v46, v3
	v_alignbit_b32 v168, v46, v109, v4
	v_alignbit_b32 v167, v109, v187, v1
	v_alignbit_b32 v166, v108, v186, v2
	v_mfma_f32_16x16x32_bf16 v[110:113], v[134:137], v[34:37], v[110:113]
	ds_read_b128 v[58:61], v86 offset:256
	ds_read_b128 v[46:49], v86 offset:320
	v_mfma_f32_16x16x32_bf16 v[108:111], v[166:169], v[26:29], v[110:113]
	s_nop 4
	v_add_u32_e32 v112, 0xe0, v87
	v_and_b32_e32 v112, 0x7ffffffe, v112
	v_mfma_f32_16x16x32_bf16 v[126:129], v[134:137], v[42:45], v[126:129]
	v_mfma_f32_16x16x32_bf16 v[122:125], v[134:137], v[22:25], v[122:125]
	v_mfma_f32_16x16x32_bf16 v[118:121], v[134:137], v[38:41], v[118:121]
	v_mfma_f32_16x16x32_bf16 v[114:117], v[134:137], v[30:33], v[114:117]
	v_mfma_f32_16x16x32_bf16 v[100:103], v[134:137], v[18:21], v[100:103]
	v_mfma_f32_16x16x32_bf16 v[96:99], v[134:137], v[14:17], v[96:99]
	v_mfma_f32_16x16x32_bf16 v[92:95], v[134:137], v[10:13], v[92:95]
	v_mfma_f32_16x16x32_bf16 v[88:91], v[134:137], v[6:9], v[88:91]
	v_mfma_f32_16x16x32_bf16 v[130:133], v[134:137], v[82:85], v[130:133]
	v_mfma_f32_16x16x32_bf16 v[78:81], v[134:137], v[74:77], v[78:81]
	v_mfma_f32_16x16x32_bf16 v[70:73], v[134:137], v[66:69], v[70:73]
	v_mfma_f32_16x16x32_bf16 v[54:57], v[134:137], v[50:53], v[54:57]
	s_waitcnt lgkmcnt(0)
	v_mfma_f32_16x16x32_bf16 v[62:65], v[134:137], v[58:61], v[62:65]
	v_lshl_add_u32 v134, v112, 1, s38
	ds_read2_b32 v[112:113], v192 offset0:3 offset1:4
	ds_read2_b32 v[186:187], v134 offset1:1
	ds_read2_b32 v[192:193], v134 offset0:1 offset1:2
	ds_read2_b32 v[194:195], v134 offset0:3 offset1:4
	v_alignbit_b32 v135, v191, v189, v1
	v_alignbit_b32 v134, v190, v188, v2
	v_mfma_f32_16x16x32_bf16 v[118:121], v[166:169], v[30:33], v[118:121]
	s_waitcnt lgkmcnt(0)
	v_alignbit_b32 v137, v113, v112, v3
	v_alignbit_b32 v136, v112, v191, v4
	v_mfma_f32_16x16x32_bf16 v[42:45], v[166:169], v[42:45], v[162:165]
	v_mfma_f32_16x16x32_bf16 v[126:129], v[166:169], v[22:25], v[126:129]
	v_mfma_f32_16x16x32_bf16 v[122:125], v[166:169], v[38:41], v[122:125]
	v_mfma_f32_16x16x32_bf16 v[114:117], v[166:169], v[34:37], v[114:117]
	v_mfma_f32_16x16x32_bf16 v[104:107], v[166:169], v[18:21], v[104:107]
	v_mfma_f32_16x16x32_bf16 v[100:103], v[166:169], v[14:17], v[100:103]
	v_mfma_f32_16x16x32_bf16 v[96:99], v[166:169], v[10:13], v[96:99]
	v_mfma_f32_16x16x32_bf16 v[92:95], v[166:169], v[6:9], v[92:95]
	v_mfma_f32_16x16x32_bf16 v[88:91], v[166:169], v[82:85], v[88:91]
	v_mfma_f32_16x16x32_bf16 v[130:133], v[166:169], v[74:77], v[130:133]
	v_mfma_f32_16x16x32_bf16 v[78:81], v[166:169], v[66:69], v[78:81]
	v_mfma_f32_16x16x32_bf16 v[70:73], v[166:169], v[50:53], v[70:73]
	v_mfma_f32_16x16x32_bf16 v[54:57], v[166:169], v[58:61], v[54:57]
	v_mfma_f32_16x16x32_bf16 v[62:65], v[166:169], v[46:49], v[62:65]
	v_alignbit_b32 v169, v195, v194, v3
	v_alignbit_b32 v168, v194, v193, v4
	v_alignbit_b32 v167, v193, v187, v1
	v_alignbit_b32 v166, v192, v186, v2
	v_mfma_f32_16x16x32_bf16 v[118:121], v[134:137], v[34:37], v[118:121]
	v_mfma_f32_16x16x32_bf16 v[162:165], v[134:137], v[22:25], v[42:45]
	s_nop 2
	ds_read_b128 v[42:45], v86 offset:384
	ds_read_b128 v[22:25], v86 offset:448
	v_mfma_f32_16x16x32_bf16 v[112:115], v[134:137], v[26:29], v[114:117]
	v_mfma_f32_16x16x32_bf16 v[116:119], v[166:169], v[26:29], v[118:121]
	s_nop 2
	v_add_u32_e32 v120, 0x100, v87
	v_add_u32_e32 v121, 0x120, v87
	v_and_b32_e32 v120, 0x7ffffffe, v120
	v_mfma_f32_16x16x32_bf16 v[126:129], v[134:137], v[38:41], v[126:129]
	v_and_b32_e32 v121, 0x7ffffffe, v121
	v_lshl_add_u32 v188, v121, 1, s38
	v_mfma_f32_16x16x32_bf16 v[122:125], v[134:137], v[30:33], v[122:125]
	v_mfma_f32_16x16x32_bf16 v[108:111], v[134:137], v[18:21], v[108:111]
	v_mfma_f32_16x16x32_bf16 v[104:107], v[134:137], v[14:17], v[104:107]
	v_mfma_f32_16x16x32_bf16 v[100:103], v[134:137], v[10:13], v[100:103]
	v_mfma_f32_16x16x32_bf16 v[96:99], v[134:137], v[6:9], v[96:99]
	v_mfma_f32_16x16x32_bf16 v[92:95], v[134:137], v[82:85], v[92:95]
	v_mfma_f32_16x16x32_bf16 v[88:91], v[134:137], v[74:77], v[88:91]
	v_mfma_f32_16x16x32_bf16 v[130:133], v[134:137], v[66:69], v[130:133]
	v_mfma_f32_16x16x32_bf16 v[78:81], v[134:137], v[50:53], v[78:81]
	v_mfma_f32_16x16x32_bf16 v[70:73], v[134:137], v[58:61], v[70:73]
	v_mfma_f32_16x16x32_bf16 v[54:57], v[134:137], v[46:49], v[54:57]
	s_waitcnt lgkmcnt(0)
	v_mfma_f32_16x16x32_bf16 v[62:65], v[134:137], v[42:45], v[62:65]
	v_lshl_add_u32 v136, v120, 1, s38
	ds_read2_b32 v[120:121], v136 offset0:3 offset1:4
	s_waitcnt lgkmcnt(0)
	v_alignbit_b32 v137, v121, v120, v3
	v_mfma_f32_16x16x32_bf16 v[38:41], v[166:169], v[38:41], v[162:165]
	ds_read2_b32 v[134:135], v136 offset0:1 offset1:2
	s_nop 1
	ds_read2_b32 v[162:163], v136 offset1:1
	ds_read2_b32 v[186:187], v188 offset1:1
	s_waitcnt lgkmcnt(0)
	v_alignbit_b32 v136, v120, v135, v4
	v_alignbit_b32 v135, v135, v163, v1
	v_alignbit_b32 v134, v134, v162, v2
	v_mfma_f32_16x16x32_bf16 v[126:129], v[166:169], v[30:33], v[126:129]
	v_mfma_f32_16x16x32_bf16 v[122:125], v[166:169], v[34:37], v[122:125]
	v_mfma_f32_16x16x32_bf16 v[162:165], v[134:137], v[30:33], v[38:41]
	v_add_u32_e32 v30, 0x140, v87
	v_and_b32_e32 v30, 0x7ffffffe, v30
	v_lshl_add_u32 v192, v30, 1, s38
	ds_read2_b32 v[30:31], v188 offset0:3 offset1:4
	v_mfma_f32_16x16x32_bf16 v[130:133], v[166:169], v[50:53], v[130:133]
	v_mfma_f32_16x16x32_bf16 v[120:123], v[134:137], v[26:29], v[122:125]
	s_nop 2
	ds_read2_b32 v[124:125], v188 offset0:1 offset1:2
	ds_read2_b32 v[188:189], v192 offset1:1
	ds_read2_b32 v[190:191], v192 offset0:1 offset1:2
	v_mfma_f32_16x16x32_bf16 v[112:115], v[166:169], v[18:21], v[112:115]
	v_mfma_f32_16x16x32_bf16 v[108:111], v[166:169], v[14:17], v[108:111]
	v_mfma_f32_16x16x32_bf16 v[104:107], v[166:169], v[10:13], v[104:107]
	v_mfma_f32_16x16x32_bf16 v[100:103], v[166:169], v[6:9], v[100:103]
	v_mfma_f32_16x16x32_bf16 v[96:99], v[166:169], v[82:85], v[96:99]
	v_mfma_f32_16x16x32_bf16 v[92:95], v[166:169], v[74:77], v[92:95]
	v_mfma_f32_16x16x32_bf16 v[88:91], v[166:169], v[66:69], v[88:91]
	v_mfma_f32_16x16x32_bf16 v[78:81], v[166:169], v[58:61], v[78:81]
	v_mfma_f32_16x16x32_bf16 v[70:73], v[166:169], v[46:49], v[70:73]
	v_mfma_f32_16x16x32_bf16 v[54:57], v[166:169], v[42:45], v[54:57]
	v_mfma_f32_16x16x32_bf16 v[62:65], v[166:169], v[22:25], v[62:65]
	s_waitcnt lgkmcnt(0)
	v_alignbit_b32 v169, v31, v30, v3
	v_alignbit_b32 v168, v30, v125, v4
	v_alignbit_b32 v167, v125, v187, v1
	v_alignbit_b32 v166, v124, v186, v2
	v_mfma_f32_16x16x32_bf16 v[126:129], v[134:137], v[34:37], v[126:129]
	ds_read_b128 v[38:41], v86 offset:512
	ds_read_b128 v[30:33], v86 offset:576
	v_mfma_f32_16x16x32_bf16 v[130:133], v[134:137], v[58:61], v[130:133]
	v_mfma_f32_16x16x32_bf16 v[124:127], v[166:169], v[26:29], v[126:129]
	v_mfma_f32_16x16x32_bf16 v[128:131], v[166:169], v[46:49], v[130:133]
	s_nop 5
	v_add_u32_e32 v132, 0x160, v87
	v_and_b32_e32 v132, 0x7ffffffe, v132
	v_mfma_f32_16x16x32_bf16 v[116:119], v[134:137], v[18:21], v[116:119]
	v_mfma_f32_16x16x32_bf16 v[112:115], v[134:137], v[14:17], v[112:115]
	v_mfma_f32_16x16x32_bf16 v[108:111], v[134:137], v[10:13], v[108:111]
	v_mfma_f32_16x16x32_bf16 v[104:107], v[134:137], v[6:9], v[104:107]
	v_mfma_f32_16x16x32_bf16 v[100:103], v[134:137], v[82:85], v[100:103]
	v_mfma_f32_16x16x32_bf16 v[96:99], v[134:137], v[74:77], v[96:99]
	v_mfma_f32_16x16x32_bf16 v[92:95], v[134:137], v[66:69], v[92:95]
	v_mfma_f32_16x16x32_bf16 v[88:91], v[134:137], v[50:53], v[88:91]
	v_mfma_f32_16x16x32_bf16 v[78:81], v[134:137], v[46:49], v[78:81]
	v_mfma_f32_16x16x32_bf16 v[70:73], v[134:137], v[42:45], v[70:73]
	v_mfma_f32_16x16x32_bf16 v[54:57], v[134:137], v[22:25], v[54:57]
	s_waitcnt lgkmcnt(0)
	v_mfma_f32_16x16x32_bf16 v[62:65], v[134:137], v[38:41], v[62:65]
	v_lshl_add_u32 v134, v132, 1, s38
	ds_read2_b32 v[132:133], v192 offset0:3 offset1:4
	ds_read2_b32 v[136:137], v134 offset1:1
	ds_read2_b32 v[186:187], v134 offset0:1 offset1:2
	ds_read2_b32 v[192:193], v134 offset0:3 offset1:4
	v_mfma_f32_16x16x32_bf16 v[34:37], v[166:169], v[34:37], v[162:165]
	s_waitcnt lgkmcnt(0)
	v_alignbit_b32 v135, v133, v132, v3
	v_alignbit_b32 v134, v132, v191, v4
	v_alignbit_b32 v133, v191, v189, v1
	v_alignbit_b32 v132, v190, v188, v2
	v_mfma_f32_16x16x32_bf16 v[120:123], v[166:169], v[18:21], v[120:123]
	v_mfma_f32_16x16x32_bf16 v[116:119], v[166:169], v[14:17], v[116:119]
	v_mfma_f32_16x16x32_bf16 v[112:115], v[166:169], v[10:13], v[112:115]
	v_mfma_f32_16x16x32_bf16 v[108:111], v[166:169], v[6:9], v[108:111]
	v_mfma_f32_16x16x32_bf16 v[104:107], v[166:169], v[82:85], v[104:107]
	v_mfma_f32_16x16x32_bf16 v[100:103], v[166:169], v[74:77], v[100:103]
	v_mfma_f32_16x16x32_bf16 v[96:99], v[166:169], v[66:69], v[96:99]
	v_mfma_f32_16x16x32_bf16 v[92:95], v[166:169], v[50:53], v[92:95]
	v_mfma_f32_16x16x32_bf16 v[88:91], v[166:169], v[58:61], v[88:91]
	v_mfma_f32_16x16x32_bf16 v[78:81], v[166:169], v[42:45], v[78:81]
	v_mfma_f32_16x16x32_bf16 v[70:73], v[166:169], v[22:25], v[70:73]
	v_mfma_f32_16x16x32_bf16 v[54:57], v[166:169], v[38:41], v[54:57]
	v_mfma_f32_16x16x32_bf16 v[62:65], v[166:169], v[30:33], v[62:65]
	v_alignbit_b32 v169, v193, v192, v3
	v_alignbit_b32 v168, v192, v187, v4
	v_alignbit_b32 v167, v187, v137, v1
	v_mfma_f32_16x16x32_bf16 v[162:165], v[132:135], v[26:29], v[34:37]
	s_nop 2
	ds_read_b128 v[34:37], v86 offset:640
	ds_read_b128 v[26:29], v86 offset:704
	v_alignbit_b32 v166, v186, v136, v2
	v_mfma_f32_16x16x32_bf16 v[124:127], v[132:135], v[18:21], v[124:127]
	v_mfma_f32_16x16x32_bf16 v[120:123], v[132:135], v[14:17], v[120:123]
	v_mfma_f32_16x16x32_bf16 v[116:119], v[132:135], v[10:13], v[116:119]
	v_mfma_f32_16x16x32_bf16 v[112:115], v[132:135], v[6:9], v[112:115]
	v_mfma_f32_16x16x32_bf16 v[108:111], v[132:135], v[82:85], v[108:111]
	v_mfma_f32_16x16x32_bf16 v[104:107], v[132:135], v[74:77], v[104:107]
	v_mfma_f32_16x16x32_bf16 v[100:103], v[132:135], v[66:69], v[100:103]
	v_mfma_f32_16x16x32_bf16 v[96:99], v[132:135], v[50:53], v[96:99]
	v_mfma_f32_16x16x32_bf16 v[92:95], v[132:135], v[58:61], v[92:95]
	v_mfma_f32_16x16x32_bf16 v[88:91], v[132:135], v[46:49], v[88:91]
	v_mfma_f32_16x16x32_bf16 v[128:131], v[132:135], v[42:45], v[128:131]
	v_mfma_f32_16x16x32_bf16 v[78:81], v[132:135], v[22:25], v[78:81]
	v_mfma_f32_16x16x32_bf16 v[70:73], v[132:135], v[38:41], v[70:73]
	v_mfma_f32_16x16x32_bf16 v[54:57], v[132:135], v[30:33], v[54:57]
	s_waitcnt lgkmcnt(0)
	v_mfma_f32_16x16x32_bf16 v[62:65], v[132:135], v[34:37], v[62:65]
	v_add_u32_e32 v132, 0x180, v87
	v_add_u32_e32 v133, 0x1a0, v87
	v_and_b32_e32 v132, 0x7ffffffe, v132
	v_and_b32_e32 v133, 0x7ffffffe, v133
	v_lshl_add_u32 v134, v132, 1, s38
	v_lshl_add_u32 v188, v133, 1, s38
	ds_read2_b32 v[132:133], v134 offset0:3 offset1:4
	v_mfma_f32_16x16x32_bf16 v[18:21], v[166:169], v[18:21], v[162:165]
	ds_read2_b32 v[136:137], v134 offset0:1 offset1:2
	s_nop 1
	ds_read2_b32 v[162:163], v134 offset1:1
	ds_read2_b32 v[186:187], v188 offset1:1
	s_waitcnt lgkmcnt(0)
	v_alignbit_b32 v135, v133, v132, v3
	v_alignbit_b32 v134, v132, v137, v4
	v_alignbit_b32 v133, v137, v163, v1
	v_alignbit_b32 v132, v136, v162, v2
	v_mfma_f32_16x16x32_bf16 v[124:127], v[166:169], v[14:17], v[124:127]
	s_nop 0
	v_mfma_f32_16x16x32_bf16 v[162:165], v[132:135], v[14:17], v[18:21]
	v_add_u32_e32 v14, 0x1c0, v87
	v_and_b32_e32 v14, 0x7ffffffe, v14
	v_lshl_add_u32 v192, v14, 1, s38
	ds_read2_b32 v[14:15], v188 offset0:3 offset1:4
	ds_read2_b32 v[136:137], v188 offset0:1 offset1:2
	ds_read2_b32 v[188:189], v192 offset1:1
	ds_read2_b32 v[190:191], v192 offset0:1 offset1:2
	v_mfma_f32_16x16x32_bf16 v[120:123], v[166:169], v[10:13], v[120:123]
	v_mfma_f32_16x16x32_bf16 v[116:119], v[166:169], v[6:9], v[116:119]
	v_mfma_f32_16x16x32_bf16 v[112:115], v[166:169], v[82:85], v[112:115]
	v_mfma_f32_16x16x32_bf16 v[108:111], v[166:169], v[74:77], v[108:111]
	v_mfma_f32_16x16x32_bf16 v[104:107], v[166:169], v[66:69], v[104:107]
	v_mfma_f32_16x16x32_bf16 v[100:103], v[166:169], v[50:53], v[100:103]
	v_mfma_f32_16x16x32_bf16 v[96:99], v[166:169], v[58:61], v[96:99]
	v_mfma_f32_16x16x32_bf16 v[92:95], v[166:169], v[46:49], v[92:95]
	v_mfma_f32_16x16x32_bf16 v[88:91], v[166:169], v[42:45], v[88:91]
	v_mfma_f32_16x16x32_bf16 v[128:131], v[166:169], v[22:25], v[128:131]
	v_mfma_f32_16x16x32_bf16 v[78:81], v[166:169], v[38:41], v[78:81]
	v_mfma_f32_16x16x32_bf16 v[70:73], v[166:169], v[30:33], v[70:73]
	v_mfma_f32_16x16x32_bf16 v[54:57], v[166:169], v[34:37], v[54:57]
	v_mfma_f32_16x16x32_bf16 v[62:65], v[166:169], v[26:29], v[62:65]
	s_waitcnt lgkmcnt(0)
	v_alignbit_b32 v169, v15, v14, v3
	v_alignbit_b32 v168, v14, v137, v4
	ds_read_b128 v[18:21], v86 offset:768
	ds_read_b128 v[14:17], v86 offset:832
	v_mfma_f32_16x16x32_bf16 v[124:127], v[132:135], v[10:13], v[124:127]
	v_alignbit_b32 v167, v137, v187, v1
	v_alignbit_b32 v166, v136, v186, v2
	v_mfma_f32_16x16x32_bf16 v[120:123], v[132:135], v[6:9], v[120:123]
	v_mfma_f32_16x16x32_bf16 v[116:119], v[132:135], v[82:85], v[116:119]
	v_mfma_f32_16x16x32_bf16 v[112:115], v[132:135], v[74:77], v[112:115]
	v_mfma_f32_16x16x32_bf16 v[108:111], v[132:135], v[66:69], v[108:111]
	v_mfma_f32_16x16x32_bf16 v[104:107], v[132:135], v[50:53], v[104:107]
	v_mfma_f32_16x16x32_bf16 v[100:103], v[132:135], v[58:61], v[100:103]
	v_mfma_f32_16x16x32_bf16 v[96:99], v[132:135], v[46:49], v[96:99]
	v_mfma_f32_16x16x32_bf16 v[92:95], v[132:135], v[42:45], v[92:95]
	v_mfma_f32_16x16x32_bf16 v[88:91], v[132:135], v[22:25], v[88:91]
	v_mfma_f32_16x16x32_bf16 v[128:131], v[132:135], v[38:41], v[128:131]
	v_mfma_f32_16x16x32_bf16 v[78:81], v[132:135], v[30:33], v[78:81]
	v_mfma_f32_16x16x32_bf16 v[70:73], v[132:135], v[34:37], v[70:73]
	v_mfma_f32_16x16x32_bf16 v[54:57], v[132:135], v[26:29], v[54:57]
	s_waitcnt lgkmcnt(0)
	v_mfma_f32_16x16x32_bf16 v[62:65], v[132:135], v[18:21], v[62:65]
	v_add_u32_e32 v132, 0x1e0, v87
	v_and_b32_e32 v132, 0x7ffffffe, v132
	v_lshl_add_u32 v134, v132, 1, s38
	ds_read2_b32 v[132:133], v192 offset0:3 offset1:4
	ds_read2_b32 v[136:137], v134 offset1:1
	ds_read2_b32 v[186:187], v134 offset0:1 offset1:2
	ds_read2_b32 v[192:193], v134 offset0:3 offset1:4
	v_mfma_f32_16x16x32_bf16 v[10:13], v[166:169], v[10:13], v[162:165]
	v_add_u32_e32 v87, 0x200, v87
	s_waitcnt lgkmcnt(0)
	v_alignbit_b32 v135, v133, v132, v3
	v_alignbit_b32 v134, v132, v191, v4
	v_alignbit_b32 v133, v191, v189, v1
	v_alignbit_b32 v132, v190, v188, v2
	v_mfma_f32_16x16x32_bf16 v[124:127], v[166:169], v[6:9], v[124:127]
	v_alignbit_b32 v189, v193, v192, v3
	v_alignbit_b32 v188, v192, v187, v4
	v_alignbit_b32 v187, v187, v137, v1
	v_mfma_f32_16x16x32_bf16 v[120:123], v[166:169], v[82:85], v[120:123]
	v_alignbit_b32 v186, v186, v136, v2
	v_mfma_f32_16x16x32_bf16 v[116:119], v[166:169], v[74:77], v[116:119]
	v_mfma_f32_16x16x32_bf16 v[112:115], v[166:169], v[66:69], v[112:115]
	v_mfma_f32_16x16x32_bf16 v[108:111], v[166:169], v[50:53], v[108:111]
	v_mfma_f32_16x16x32_bf16 v[104:107], v[166:169], v[58:61], v[104:107]
	v_mfma_f32_16x16x32_bf16 v[100:103], v[166:169], v[46:49], v[100:103]
	v_mfma_f32_16x16x32_bf16 v[96:99], v[166:169], v[42:45], v[96:99]
	v_mfma_f32_16x16x32_bf16 v[92:95], v[166:169], v[22:25], v[92:95]
	v_mfma_f32_16x16x32_bf16 v[88:91], v[166:169], v[38:41], v[88:91]
	v_mfma_f32_16x16x32_bf16 v[128:131], v[166:169], v[30:33], v[128:131]
	v_mfma_f32_16x16x32_bf16 v[78:81], v[166:169], v[34:37], v[78:81]
	v_mfma_f32_16x16x32_bf16 v[70:73], v[166:169], v[26:29], v[70:73]
	v_mfma_f32_16x16x32_bf16 v[54:57], v[166:169], v[18:21], v[54:57]
	v_mfma_f32_16x16x32_bf16 v[62:65], v[166:169], v[14:17], v[62:65]
	v_mfma_f32_16x16x32_bf16 v[162:165], v[132:135], v[6:9], v[10:13]
	s_nop 2
	ds_read_b128 v[10:13], v86 offset:896
	ds_read_b128 v[6:9], v86 offset:960
	v_add_u32_e32 v86, 0x400, v86
	v_mfma_f32_16x16x32_bf16 v[124:127], v[132:135], v[82:85], v[124:127]
	v_mfma_f32_16x16x32_bf16 v[120:123], v[132:135], v[74:77], v[120:123]
	v_mfma_f32_16x16x32_bf16 v[116:119], v[132:135], v[66:69], v[116:119]
	v_mfma_f32_16x16x32_bf16 v[112:115], v[132:135], v[50:53], v[112:115]
	v_mfma_f32_16x16x32_bf16 v[108:111], v[132:135], v[58:61], v[108:111]
	v_mfma_f32_16x16x32_bf16 v[104:107], v[132:135], v[46:49], v[104:107]
	v_mfma_f32_16x16x32_bf16 v[100:103], v[132:135], v[42:45], v[100:103]
	v_mfma_f32_16x16x32_bf16 v[96:99], v[132:135], v[22:25], v[96:99]
	v_mfma_f32_16x16x32_bf16 v[92:95], v[132:135], v[38:41], v[92:95]
	v_mfma_f32_16x16x32_bf16 v[88:91], v[132:135], v[30:33], v[88:91]
	v_mfma_f32_16x16x32_bf16 v[166:169], v[132:135], v[34:37], v[128:131]
	v_mfma_f32_16x16x32_bf16 v[78:81], v[132:135], v[26:29], v[78:81]
	v_mfma_f32_16x16x32_bf16 v[70:73], v[132:135], v[18:21], v[70:73]
	v_mfma_f32_16x16x32_bf16 v[54:57], v[132:135], v[14:17], v[54:57]
	s_waitcnt lgkmcnt(0)
	v_mfma_f32_16x16x32_bf16 v[62:65], v[132:135], v[10:13], v[62:65]
	v_mfma_f32_16x16x32_bf16 v[130:133], v[186:189], v[82:85], v[162:165]
	v_mfma_f32_16x16x32_bf16 v[126:129], v[186:189], v[74:77], v[124:127]
	v_mfma_f32_16x16x32_bf16 v[122:125], v[186:189], v[66:69], v[120:123]
	v_mfma_f32_16x16x32_bf16 v[118:121], v[186:189], v[50:53], v[116:119]
	v_mfma_f32_16x16x32_bf16 v[114:117], v[186:189], v[58:61], v[112:115]
	v_mfma_f32_16x16x32_bf16 v[110:113], v[186:189], v[46:49], v[108:111]
	v_mfma_f32_16x16x32_bf16 v[106:109], v[186:189], v[42:45], v[104:107]
	v_mfma_f32_16x16x32_bf16 v[102:105], v[186:189], v[22:25], v[100:103]
	v_mfma_f32_16x16x32_bf16 v[98:101], v[186:189], v[38:41], v[96:99]
	v_mfma_f32_16x16x32_bf16 v[94:97], v[186:189], v[30:33], v[92:95]
	v_mfma_f32_16x16x32_bf16 v[90:93], v[186:189], v[34:37], v[88:91]
	v_mfma_f32_16x16x32_bf16 v[82:85], v[186:189], v[26:29], v[166:169]
	v_mfma_f32_16x16x32_bf16 v[78:81], v[186:189], v[18:21], v[78:81]
	v_mfma_f32_16x16x32_bf16 v[70:73], v[186:189], v[14:17], v[70:73]
	v_mfma_f32_16x16x32_bf16 v[54:57], v[186:189], v[10:13], v[54:57]
	v_mfma_f32_16x16x32_bf16 v[62:65], v[186:189], v[6:9], v[62:65]
	s_cbranch_scc1 .LBB0_2210
	v_add_u32_e32 v86, 0x1c10, v173
	v_add_u32_e32 v88, 0x1c14, v173
	v_add_u32_e32 v89, 0x1c1c, v173
	ds_read2_b32 v[86:87], v86 offset1:1
	ds_read2_b32 v[134:135], v88 offset1:1
	ds_read2_b32 v[88:89], v89 offset1:1
	v_add_u32_e32 v136, 0x1c50, v173
	v_add_u32_e32 v137, 0x1c54, v173
	ds_read2_b32 v[162:163], v136 offset1:1
	ds_read2_b32 v[164:165], v137 offset1:1
	s_waitcnt lgkmcnt(0)
	v_alignbit_b32 v87, v135, v87, v1
	v_alignbit_b32 v89, v89, v88, v3
	v_alignbit_b32 v88, v88, v135, v4
	v_alignbit_b32 v86, v134, v86, v2
	v_add_u32_e32 v134, 0x1c9c, v173
	s_add_i32 s2, s12, 0x400
	v_mfma_f32_16x16x32_bf16 v[130:133], v[86:89], v[74:77], v[130:133]
	v_add_u32_e32 v74, 0x1c5c, v173
	v_add_u32_e32 v76, 0x1c90, v173
	v_add_u32_e32 v77, 0x1c94, v173
	ds_read2_b32 v[74:75], v74 offset1:1
	ds_read2_b32 v[166:167], v76 offset1:1
	ds_read2_b32 v[168:169], v77 offset1:1
	ds_read2_b32 v[186:187], v134 offset1:1
	v_mfma_f32_16x16x32_bf16 v[126:129], v[86:89], v[66:69], v[126:129]
	s_waitcnt lgkmcnt(0)
	v_alignbit_b32 v77, v75, v74, v3
	v_alignbit_b32 v76, v74, v165, v4
	v_alignbit_b32 v75, v165, v163, v1
	v_alignbit_b32 v74, v164, v162, v2
	v_mfma_f32_16x16x32_bf16 v[134:137], v[86:89], v[34:37], v[94:97]
	v_add_u32_e32 v162, 0x1d10, v173
	v_add_u32_e32 v206, 0x1e9c, v173
	s_ashr_i32 s18, s2, 3
	v_mfma_f32_16x16x32_bf16 v[94:97], v[86:89], v[26:29], v[90:93]
	s_ashr_i32 s19, s18, 31
	s_lshl_b64 s[18:19], s[18:19], 7
	s_lshl_b64 s[12:13], s[12:13], 16
	v_mfma_f32_16x16x32_bf16 v[90:93], v[74:77], v[66:69], v[130:133]
	v_alignbit_b32 v69, v187, v186, v3
	v_alignbit_b32 v68, v186, v169, v4
	v_alignbit_b32 v67, v169, v167, v1
	v_alignbit_b32 v66, v168, v166, v2
	v_mfma_f32_16x16x32_bf16 v[98:101], v[86:89], v[30:33], v[98:101]
	s_andn2_b64 vcc, exec, s[14:15]
	v_mfma_f32_16x16x32_bf16 v[102:105], v[86:89], v[38:41], v[102:105]
	v_mfma_f32_16x16x32_bf16 v[130:133], v[74:77], v[34:37], v[98:101]
	v_mfma_f32_16x16x32_bf16 v[98:101], v[74:77], v[26:29], v[134:137]
	v_mfma_f32_16x16x32_bf16 v[134:137], v[66:69], v[50:53], v[90:93]
	s_nop 2
	v_add_u32_e32 v90, 0x1cdc, v173
	v_mfma_f32_16x16x32_bf16 v[122:125], v[86:89], v[50:53], v[122:125]
	v_add_u32_e32 v92, 0x1cd0, v173
	v_add_u32_e32 v93, 0x1cd4, v173
	v_mfma_f32_16x16x32_bf16 v[126:129], v[74:77], v[50:53], v[126:129]
	ds_read_b128 v[50:53], v171 offset:4032
	ds_read2_b32 v[90:91], v90 offset1:1
	ds_read2_b32 v[186:187], v93 offset1:1
	ds_read2_b32 v[188:189], v92 offset1:1
	ds_read2_b32 v[190:191], v162 offset1:1
	s_waitcnt lgkmcnt(0)
	v_alignbit_b32 v93, v91, v90, v3
	v_mfma_f32_16x16x32_bf16 v[102:105], v[74:77], v[30:33], v[102:105]
	v_alignbit_b32 v92, v90, v187, v4
	v_alignbit_b32 v91, v187, v189, v1
	v_alignbit_b32 v90, v186, v188, v2
	v_mfma_f32_16x16x32_bf16 v[106:109], v[86:89], v[22:25], v[106:109]
	v_add_u32_e32 v186, 0x1d50, v173
	v_add_u32_e32 v188, 0x1d54, v173
	v_mfma_f32_16x16x32_bf16 v[118:121], v[86:89], v[58:61], v[118:121]
	v_mfma_f32_16x16x32_bf16 v[110:113], v[86:89], v[42:45], v[110:113]
	v_mfma_f32_16x16x32_bf16 v[166:169], v[66:69], v[34:37], v[102:105]
	s_nop 2
	v_add_u32_e32 v102, 0x1d14, v173
	v_add_u32_e32 v104, 0x1d1c, v173
	v_mfma_f32_16x16x32_bf16 v[106:109], v[74:77], v[38:41], v[106:109]
	ds_read2_b32 v[102:103], v102 offset1:1
	ds_read2_b32 v[104:105], v104 offset1:1
	ds_read2_b32 v[186:187], v186 offset1:1
	ds_read2_b32 v[188:189], v188 offset1:1
	v_mfma_f32_16x16x32_bf16 v[122:125], v[74:77], v[58:61], v[122:125]
	v_mfma_f32_16x16x32_bf16 v[114:117], v[86:89], v[46:49], v[114:117]
	v_mfma_f32_16x16x32_bf16 v[118:121], v[74:77], v[46:49], v[118:121]
	v_mfma_f32_16x16x32_bf16 v[110:113], v[74:77], v[22:25], v[110:113]
	v_mfma_f32_16x16x32_bf16 v[126:129], v[66:69], v[58:61], v[126:129]
	v_mfma_f32_16x16x32_bf16 v[162:165], v[66:69], v[30:33], v[106:109]
	v_mfma_f32_16x16x32_bf16 v[106:109], v[66:69], v[26:29], v[130:133]
	v_mfma_f32_16x16x32_bf16 v[130:133], v[90:93], v[58:61], v[134:137]
	s_waitcnt lgkmcnt(0)
	v_alignbit_b32 v58, v102, v190, v2
	v_add_u32_e32 v102, 0x1d5c, v173
	v_alignbit_b32 v61, v105, v104, v3
	v_mfma_f32_16x16x32_bf16 v[122:125], v[66:69], v[46:49], v[122:125]
	v_alignbit_b32 v60, v104, v103, v4
	v_alignbit_b32 v59, v103, v191, v1
	v_add_u32_e32 v104, 0x1d90, v173
	v_add_u32_e32 v105, 0x1d94, v173
	v_add_u32_e32 v134, 0x1d9c, v173
	ds_read2_b32 v[102:103], v102 offset1:1
	ds_read2_b32 v[190:191], v104 offset1:1
	ds_read2_b32 v[192:193], v105 offset1:1
	ds_read2_b32 v[194:195], v134 offset1:1
	v_mfma_f32_16x16x32_bf16 v[114:117], v[74:77], v[42:45], v[114:117]
	s_waitcnt lgkmcnt(0)
	v_alignbit_b32 v105, v103, v102, v3
	v_alignbit_b32 v104, v102, v189, v4
	v_alignbit_b32 v102, v188, v186, v2
	v_mfma_f32_16x16x32_bf16 v[118:121], v[66:69], v[42:45], v[118:121]
	v_add_u32_e32 v188, 0x1ddc, v173
	v_alignbit_b32 v103, v189, v187, v1
	v_add_u32_e32 v186, 0x1dd0, v173
	v_mfma_f32_16x16x32_bf16 v[110:113], v[66:69], v[38:41], v[110:113]
	v_add_u32_e32 v187, 0x1dd4, v173
	v_add_u32_e32 v189, 0x1e10, v173
	v_mfma_f32_16x16x32_bf16 v[122:125], v[90:93], v[42:45], v[122:125]
	v_mfma_f32_16x16x32_bf16 v[114:117], v[66:69], v[22:25], v[114:117]
	v_mfma_f32_16x16x32_bf16 v[126:129], v[90:93], v[46:49], v[126:129]
	v_mfma_f32_16x16x32_bf16 v[118:121], v[90:93], v[22:25], v[118:121]
	v_mfma_f32_16x16x32_bf16 v[134:137], v[90:93], v[30:33], v[110:113]
	s_nop 2
	v_alignbit_b32 v112, v194, v193, v4
	v_alignbit_b32 v111, v193, v191, v1
	v_alignbit_b32 v110, v192, v190, v2
	v_mfma_f32_16x16x32_bf16 v[130:133], v[58:61], v[46:49], v[130:133]
	ds_read2_b32 v[46:47], v188 offset1:1
	ds_read2_b32 v[190:191], v187 offset1:1
	ds_read2_b32 v[192:193], v186 offset1:1
	ds_read2_b32 v[198:199], v189 offset1:1
	v_alignbit_b32 v113, v195, v194, v3
	s_waitcnt lgkmcnt(0)
	v_alignbit_b32 v49, v47, v46, v3
	v_mfma_f32_16x16x32_bf16 v[186:189], v[58:61], v[22:25], v[122:125]
	v_alignbit_b32 v48, v46, v191, v4
	v_alignbit_b32 v47, v191, v193, v1
	v_alignbit_b32 v46, v190, v192, v2
	v_add_u32_e32 v122, 0x1e14, v173
	v_mfma_f32_16x16x32_bf16 v[114:117], v[90:93], v[38:41], v[114:117]
	v_add_u32_e32 v123, 0x1e1c, v173
	v_mfma_f32_16x16x32_bf16 v[190:193], v[58:61], v[38:41], v[118:121]
	s_nop 2
	ds_read2_b32 v[118:119], v122 offset1:1
	ds_read2_b32 v[120:121], v123 offset1:1
	v_add_u32_e32 v122, 0x1e50, v173
	v_add_u32_e32 v123, 0x1e54, v173
	v_mfma_f32_16x16x32_bf16 v[162:165], v[90:93], v[34:37], v[162:165]
	ds_read2_b32 v[200:201], v122 offset1:1
	ds_read2_b32 v[202:203], v123 offset1:1
	v_mfma_f32_16x16x32_bf16 v[166:169], v[90:93], v[26:29], v[166:169]
	v_mfma_f32_16x16x32_bf16 v[126:129], v[58:61], v[42:45], v[126:129]
	v_mfma_f32_16x16x32_bf16 v[130:133], v[102:105], v[42:45], v[130:133]
	s_waitcnt lgkmcnt(0)
	v_alignbit_b32 v42, v202, v200, v2
	v_add_u32_e32 v200, 0x1ed4, v173
	v_add_u32_e32 v202, 0x1edc, v173
	v_mfma_f32_16x16x32_bf16 v[194:197], v[58:61], v[30:33], v[114:117]
	v_alignbit_b32 v43, v203, v201, v1
	s_nop 1
	v_alignbit_b32 v114, v118, v198, v2
	v_add_u32_e32 v198, 0x1e5c, v173
	v_alignbit_b32 v117, v121, v120, v3
	v_alignbit_b32 v116, v120, v119, v4
	v_alignbit_b32 v115, v119, v199, v1
	v_mfma_f32_16x16x32_bf16 v[122:125], v[58:61], v[26:29], v[162:165]
	s_nop 2
	v_add_u32_e32 v164, 0x1e90, v173
	v_add_u32_e32 v165, 0x1e94, v173
	v_mfma_f32_16x16x32_bf16 v[118:121], v[58:61], v[18:21], v[166:169]
	ds_read2_b32 v[162:163], v198 offset1:1
	ds_read2_b32 v[198:199], v164 offset1:1
	ds_read2_b32 v[204:205], v165 offset1:1
	ds_read2_b32 v[166:167], v206 offset1:1
	s_waitcnt lgkmcnt(0)
	v_alignbit_b32 v45, v163, v162, v3
	v_alignbit_b32 v44, v162, v203, v4
	v_mfma_f32_16x16x32_bf16 v[162:165], v[102:105], v[22:25], v[126:129]
	v_mfma_f32_16x16x32_bf16 v[130:133], v[110:113], v[22:25], v[130:133]
	v_mov_b32_e32 v22, s37
	v_or3_b32 v23, s19, 0, 0
	v_or3_b32 v22, s18, v140, v22
	v_lshlrev_b64 v[22:23], 12, v[22:23]
	v_alignbit_b32 v126, v204, v198, v2
	v_add_u32_e32 v198, 0x1ed0, v173
	v_add_u32_e32 v204, 0x1f10, v173
	v_lshl_add_u64 v[234:235], v[160:161], 0, v[22:23]
	v_mfma_f32_16x16x32_bf16 v[134:137], v[58:61], v[34:37], v[134:137]
	v_alignbit_b32 v128, v166, v205, v4
	v_alignbit_b32 v127, v205, v199, v1
	ds_read2_b32 v[198:199], v198 offset1:1
	ds_read2_b32 v[200:201], v200 offset1:1
	ds_read2_b32 v[202:203], v202 offset1:1
	ds_read2_b32 v[204:205], v204 offset1:1
	global_load_dwordx2 v[236:237], v[234:235], off
	global_load_dword v22, v139, s[16:17] offset:2048
	v_alignbit_b32 v129, v167, v166, v3
	v_mfma_f32_16x16x32_bf16 v[166:169], v[102:105], v[38:41], v[186:189]
	v_add_u32_e32 v24, 0x1f1c, v173
	v_add_u32_e32 v23, 0x1f14, v173
	v_mfma_f32_16x16x32_bf16 v[186:189], v[102:105], v[30:33], v[190:193]
	v_mfma_f32_16x16x32_bf16 v[190:193], v[102:105], v[34:37], v[194:197]
	v_mfma_f32_16x16x32_bf16 v[194:197], v[102:105], v[26:29], v[134:137]
	v_mfma_f32_16x16x32_bf16 v[134:137], v[110:113], v[38:41], v[162:165]
	v_mfma_f32_16x16x32_bf16 v[162:165], v[110:113], v[30:33], v[166:169]
	v_mfma_f32_16x16x32_bf16 v[38:41], v[46:49], v[38:41], v[130:133]
	s_waitcnt lgkmcnt(0)
	s_nop 0
	v_alignbit_b32 v169, v203, v202, v3
	v_alignbit_b32 v168, v202, v201, v4
	v_alignbit_b32 v167, v201, v199, v1
	v_mfma_f32_16x16x32_bf16 v[130:133], v[46:49], v[30:33], v[134:137]
	v_alignbit_b32 v166, v200, v198, v2
	v_add_u32_e32 v200, 0x1f50, v173
	v_add_u32_e32 v201, 0x1f54, v173
	ds_read2_b32 v[24:25], v24 offset1:1
	ds_read2_b32 v[198:199], v23 offset1:1
	ds_read2_b32 v[202:203], v200 offset1:1
	ds_read2_b32 v[210:211], v201 offset1:1
	v_mfma_f32_16x16x32_bf16 v[134:137], v[46:49], v[34:37], v[162:165]
	v_add_u32_e32 v23, 0x1f5c, v173
	s_waitcnt lgkmcnt(0)
	v_alignbit_b32 v201, v25, v24, v3
	v_alignbit_b32 v200, v24, v199, v4
	global_load_dwordx2 v[164:165], v[234:235], off offset:64
	v_mfma_f32_16x16x32_bf16 v[30:33], v[114:117], v[30:33], v[38:41]
	v_add_u32_e32 v162, 0x1f90, v173
	v_alignbit_b32 v199, v199, v205, v1
	v_alignbit_b32 v198, v198, v204, v2
	v_mfma_f32_16x16x32_bf16 v[38:41], v[114:117], v[34:37], v[130:133]
	v_add_u32_e32 v204, 0x1f94, v173
	v_add_u32_e32 v205, 0x1f9c, v173
	ds_read2_b32 v[24:25], v23 offset1:1
	ds_read2_b32 v[162:163], v162 offset1:1
	ds_read2_b32 v[214:215], v204 offset1:1
	ds_read2_b32 v[212:213], v205 offset1:1
	v_add_u32_e32 v23, 0x1fd0, v173
	global_load_dwordx2 v[130:131], v[234:235], off offset:128
	v_mfma_f32_16x16x32_bf16 v[186:189], v[110:113], v[34:37], v[186:189]
	s_waitcnt lgkmcnt(0)
	v_alignbit_b32 v205, v25, v24, v3
	v_alignbit_b32 v204, v24, v211, v4
	v_add_u32_e32 v24, 0x1fd4, v173
	v_mfma_f32_16x16x32_bf16 v[30:33], v[42:45], v[34:37], v[30:33]
	v_add_u32_e32 v25, 0x1fdc, v173
	v_alignbit_b32 v203, v211, v203, v1
	v_alignbit_b32 v202, v210, v202, v2
	v_mfma_f32_16x16x32_bf16 v[34:37], v[42:45], v[26:29], v[38:41]
	s_nop 2
	ds_read2_b32 v[38:39], v23 offset1:1
	ds_read2_b32 v[40:41], v24 offset1:1
	ds_read2_b32 v[132:133], v25 offset1:1
	v_alignbit_b32 v213, v213, v212, v3
	v_alignbit_b32 v212, v212, v215, v4
	v_alignbit_b32 v211, v215, v163, v1
	v_alignbit_b32 v210, v214, v162, v2
	s_waitcnt lgkmcnt(0)
	v_alignbit_b32 v215, v41, v39, v1
	v_alignbit_b32 v214, v40, v38, v2
	global_load_dwordx2 v[38:39], v[234:235], off offset:192
	global_load_dwordx2 v[238:239], v[234:235], off offset:256
	global_load_dwordx2 v[240:241], v[234:235], off offset:320
	global_load_dwordx2 v[242:243], v[234:235], off offset:384
	global_load_dwordx2 v[162:163], v[234:235], off offset:448
	v_mfma_f32_16x16x32_bf16 v[190:193], v[110:113], v[26:29], v[190:193]
	v_alignbit_b32 v217, v133, v132, v3
	v_alignbit_b32 v216, v132, v41, v4
	v_mfma_f32_16x16x32_bf16 v[186:189], v[46:49], v[26:29], v[186:189]
	v_mfma_f32_16x16x32_bf16 v[206:209], v[114:117], v[26:29], v[134:137]
	s_nop 2
	global_load_dwordx2 v[136:137], v[234:235], off offset:512
	global_load_dwordx2 v[134:135], v[234:235], off offset:576
	global_load_dwordx2 v[132:133], v[234:235], off offset:640
	global_load_dwordx2 v[40:41], v[234:235], off offset:704
	ds_read2_b64 v[222:225], v185 offset1:8
	v_mfma_f32_16x16x32_bf16 v[24:27], v[126:129], v[26:29], v[30:33]
	v_mfma_f32_16x16x32_bf16 v[24:27], v[166:169], v[18:21], v[24:27]
	s_waitcnt vmcnt(0)
	s_nop 0
	v_lshlrev_b32_e32 v30, 16, v236
	v_and_b32_e32 v31, 0xffff0000, v236
	v_mfma_f32_16x16x32_bf16 v[24:27], v[198:201], v[14:17], v[24:27]
	v_mfma_f32_16x16x32_bf16 v[226:229], v[202:205], v[10:13], v[24:27]
	v_mfma_f32_16x16x32_bf16 v[218:221], v[126:129], v[18:21], v[34:37]
	s_waitcnt lgkmcnt(0)
	s_nop 4
	v_lshlrev_b32_e32 v26, 16, v222
	v_and_b32_e32 v27, 0xffff0000, v222
	global_load_dwordx2 v[36:37], v[234:235], off offset:768
	global_load_dwordx2 v[32:33], v[234:235], off offset:832
	global_load_dwordx2 v[28:29], v[234:235], off offset:896
	global_load_dwordx2 v[24:25], v[234:235], off offset:960
	v_mfma_f32_16x16x32_bf16 v[226:229], v[210:213], v[6:9], v[226:229]
	v_lshlrev_b32_e32 v34, 16, v237
	v_and_b32_e32 v35, 0xffff0000, v237
	v_mfma_f32_16x16x32_bf16 v[218:221], v[166:169], v[14:17], v[218:221]
	v_mfma_f32_16x16x32_bf16 v[206:209], v[42:45], v[18:21], v[206:209]
	v_mfma_f32_16x16x32_bf16 v[214:217], v[214:217], v[50:53], v[226:229]
	v_mfma_f32_16x16x32_bf16 v[218:221], v[198:201], v[10:13], v[218:221]
	v_mfma_f32_16x16x32_bf16 v[206:209], v[126:129], v[14:17], v[206:209]
	s_nop 5
	v_fma_f32 v26, v22, v26, v214
	v_fma_f32 v27, v22, v27, v215
	v_pk_mul_f32 v[26:27], v[26:27], v[30:31]
	v_lshlrev_b32_e32 v30, 16, v223
	v_mfma_f32_16x16x32_bf16 v[186:189], v[114:117], v[18:21], v[186:189]
	v_and_b32_e32 v31, 0xffff0000, v223
	v_pk_fma_f32 v[30:31], v[22:23], v[30:31], v[216:217] op_sel_hi:[0,1,1]
	v_pk_mul_f32 v[30:31], v[30:31], v[34:35]
	v_mfma_f32_16x16x32_bf16 v[214:217], v[202:205], v[6:9], v[218:221]
	v_cvt_pk_bf16_f32 v26, v26, v27
	v_cvt_pk_bf16_f32 v27, v30, v31
	v_lshlrev_b32_e32 v30, 16, v224
	v_mfma_f32_16x16x32_bf16 v[206:209], v[166:169], v[10:13], v[206:209]
	v_and_b32_e32 v31, 0xffff0000, v224
	v_lshlrev_b32_e32 v34, 16, v164
	v_and_b32_e32 v35, 0xffff0000, v164
	v_mfma_f32_16x16x32_bf16 v[186:189], v[42:45], v[14:17], v[186:189]
	v_lshlrev_b32_e32 v164, 16, v165
	v_and_b32_e32 v165, 0xffff0000, v165
	v_mfma_f32_16x16x32_bf16 v[210:213], v[210:213], v[50:53], v[214:217]
	v_mfma_f32_16x16x32_bf16 v[206:209], v[198:201], v[6:9], v[206:209]
	s_nop 1
	ds_read2_b64 v[214:217], v185 offset0:16 offset1:24
	s_nop 3
	v_pk_fma_f32 v[30:31], v[22:23], v[30:31], v[210:211] op_sel_hi:[0,1,1]
	v_pk_mul_f32 v[30:31], v[30:31], v[34:35]
	v_mfma_f32_16x16x32_bf16 v[186:189], v[126:129], v[10:13], v[186:189]
	v_lshlrev_b32_e32 v34, 16, v225
	v_and_b32_e32 v35, 0xffff0000, v225
	v_pk_fma_f32 v[34:35], v[22:23], v[34:35], v[212:213] op_sel_hi:[0,1,1]
	v_mfma_f32_16x16x32_bf16 v[202:205], v[202:205], v[50:53], v[206:209]
	v_mul_f32_e64 v34, v34, v164
	v_mul_f32_e64 v35, v35, v165
	v_cvt_pk_bf16_f32 v30, v30, v31
	v_cvt_pk_bf16_f32 v31, v34, v35
	v_mfma_f32_16x16x32_bf16 v[190:193], v[46:49], v[18:21], v[190:193]
	s_waitcnt lgkmcnt(0)
	v_lshlrev_b32_e32 v34, 16, v214
	v_and_b32_e32 v35, 0xffff0000, v214
	v_lshlrev_b32_e32 v164, 16, v130
	v_mfma_f32_16x16x32_bf16 v[186:189], v[166:169], v[6:9], v[186:189]
	v_and_b32_e32 v165, 0xffff0000, v130
	v_pk_fma_f32 v[34:35], v[22:23], v[34:35], v[202:203] op_sel_hi:[0,1,1]
	v_pk_mul_f32 v[34:35], v[34:35], v[164:165]
	v_mfma_f32_16x16x32_bf16 v[190:193], v[114:117], v[14:17], v[190:193]
	v_lshlrev_b32_e32 v164, 16, v215
	v_and_b32_e32 v165, 0xffff0000, v215
	v_lshlrev_b32_e32 v130, 16, v131
	v_mfma_f32_16x16x32_bf16 v[186:189], v[198:201], v[50:53], v[186:189]
	v_and_b32_e32 v131, 0xffff0000, v131
	v_pk_fma_f32 v[164:165], v[22:23], v[164:165], v[204:205] op_sel_hi:[0,1,1]
	v_pk_mul_f32 v[130:131], v[164:165], v[130:131]
	v_cvt_pk_bf16_f32 v34, v34, v35
	v_cvt_pk_bf16_f32 v35, v130, v131
	v_lshlrev_b32_e32 v130, 16, v216
	v_and_b32_e32 v131, 0xffff0000, v216
	v_mfma_f32_16x16x32_bf16 v[190:193], v[42:45], v[10:13], v[190:193]
	v_lshlrev_b32_e32 v164, 16, v38
	v_and_b32_e32 v165, 0xffff0000, v38
	v_pk_fma_f32 v[130:131], v[22:23], v[130:131], v[186:187] op_sel_hi:[0,1,1]
	v_pk_mul_f32 v[130:131], v[130:131], v[164:165]
	v_lshlrev_b32_e32 v164, 16, v39
	v_cvt_pk_bf16_f32 v38, v130, v131
	v_lshlrev_b32_e32 v130, 16, v217
	v_and_b32_e32 v131, 0xffff0000, v217
	v_pk_fma_f32 v[130:131], v[22:23], v[130:131], v[188:189] op_sel_hi:[0,1,1]
	v_mfma_f32_16x16x32_bf16 v[186:189], v[126:129], v[6:9], v[190:193]
	v_and_b32_e32 v165, 0xffff0000, v39
	v_pk_mul_f32 v[130:131], v[130:131], v[164:165]
	ds_read2_b64 v[198:201], v185 offset0:32 offset1:40
	v_mfma_f32_16x16x32_bf16 v[164:167], v[166:169], v[50:53], v[186:189]
	v_cvt_pk_bf16_f32 v39, v130, v131
	v_lshlrev_b32_e32 v190, 16, v238
	v_and_b32_e32 v191, 0xffff0000, v238
	v_mfma_f32_16x16x32_bf16 v[186:189], v[110:113], v[18:21], v[194:197]
	s_waitcnt lgkmcnt(0)
	v_lshlrev_b32_e32 v130, 16, v198
	v_and_b32_e32 v131, 0xffff0000, v198
	s_nop 0
	v_pk_fma_f32 v[130:131], v[22:23], v[130:131], v[164:165] op_sel_hi:[0,1,1]
	v_mfma_f32_16x16x32_bf16 v[186:189], v[46:49], v[14:17], v[186:189]
	v_lshlrev_b32_e32 v164, 16, v199
	v_and_b32_e32 v165, 0xffff0000, v199
	v_pk_mul_f32 v[130:131], v[130:131], v[190:191]
	v_mfma_f32_16x16x32_bf16 v[122:125], v[102:105], v[18:21], v[122:125]
	v_fma_f32 v190, v22, v164, v166
	v_fma_f32 v191, v22, v165, v167
	v_lshlrev_b32_e32 v168, 16, v239
	v_and_b32_e32 v169, 0xffff0000, v239
	v_mfma_f32_16x16x32_bf16 v[164:167], v[114:117], v[10:13], v[186:189]
	v_mul_f32_e64 v168, v190, v168
	v_mul_f32_e64 v169, v191, v169
	v_cvt_pk_bf16_f32 v130, v130, v131
	v_cvt_pk_bf16_f32 v131, v168, v169
	v_mfma_f32_16x16x32_bf16 v[122:125], v[110:113], v[14:17], v[122:125]
	v_lshlrev_b32_e32 v168, 16, v200
	v_and_b32_e32 v169, 0xffff0000, v200
	v_lshlrev_b32_e32 v186, 16, v240
	v_mfma_f32_16x16x32_bf16 v[118:121], v[102:105], v[14:17], v[118:121]
	v_and_b32_e32 v187, 0xffff0000, v240
	v_mfma_f32_16x16x32_bf16 v[164:167], v[42:45], v[6:9], v[164:167]
	v_mfma_f32_16x16x32_bf16 v[122:125], v[46:49], v[10:13], v[122:125]
	v_mfma_f32_16x16x32_bf16 v[106:109], v[90:93], v[18:21], v[106:109]
	v_mfma_f32_16x16x32_bf16 v[118:121], v[110:113], v[10:13], v[118:121]
	v_mfma_f32_16x16x32_bf16 v[126:129], v[126:129], v[50:53], v[164:167]
	v_mfma_f32_16x16x32_bf16 v[122:125], v[114:117], v[6:9], v[122:125]
	s_nop 2
	ds_read2_b64 v[164:167], v185 offset0:48 offset1:56
	s_nop 2
	v_pk_fma_f32 v[126:127], v[22:23], v[168:169], v[126:127] op_sel_hi:[0,1,1]
	v_lshlrev_b32_e32 v168, 16, v201
	v_mfma_f32_16x16x32_bf16 v[106:109], v[58:61], v[14:17], v[106:109]
	v_and_b32_e32 v169, 0xffff0000, v201
	v_pk_mul_f32 v[126:127], v[126:127], v[186:187]
	v_lshlrev_b32_e32 v186, 16, v241
	v_mfma_f32_16x16x32_bf16 v[118:121], v[46:49], v[6:9], v[118:121]
	v_and_b32_e32 v187, 0xffff0000, v241
	v_pk_fma_f32 v[128:129], v[22:23], v[168:169], v[128:129] op_sel_hi:[0,1,1]
	v_pk_mul_f32 v[128:129], v[128:129], v[186:187]
	v_mfma_f32_16x16x32_bf16 v[42:45], v[42:45], v[50:53], v[122:125]
	v_cvt_pk_bf16_f32 v126, v126, v127
	v_cvt_pk_bf16_f32 v127, v128, v129
	s_waitcnt lgkmcnt(0)
	v_lshlrev_b32_e32 v128, 16, v164
	v_mfma_f32_16x16x32_bf16 v[106:109], v[102:105], v[10:13], v[106:109]
	v_and_b32_e32 v129, 0xffff0000, v164
	v_lshlrev_b32_e32 v122, 16, v165
	v_and_b32_e32 v123, 0xffff0000, v165
	v_mfma_f32_16x16x32_bf16 v[114:117], v[114:117], v[50:53], v[118:121]
	v_lshlrev_b32_e32 v168, 16, v242
	v_and_b32_e32 v169, 0xffff0000, v242
	v_pk_fma_f32 v[42:43], v[22:23], v[128:129], v[42:43] op_sel_hi:[0,1,1]
	v_lshlrev_b32_e32 v124, 16, v243
	v_and_b32_e32 v125, 0xffff0000, v243
	v_pk_fma_f32 v[44:45], v[22:23], v[122:123], v[44:45] op_sel_hi:[0,1,1]
	v_pk_mul_f32 v[42:43], v[42:43], v[168:169]
	v_pk_mul_f32 v[44:45], v[44:45], v[124:125]
	v_cvt_pk_bf16_f32 v42, v42, v43
	v_cvt_pk_bf16_f32 v43, v44, v45
	v_lshlrev_b32_e32 v44, 16, v166
	v_and_b32_e32 v45, 0xffff0000, v166
	v_mfma_f32_16x16x32_bf16 v[106:109], v[110:113], v[6:9], v[106:109]
	v_lshlrev_b32_e32 v118, 16, v162
	v_and_b32_e32 v119, 0xffff0000, v162
	v_pk_fma_f32 v[44:45], v[22:23], v[44:45], v[114:115] op_sel_hi:[0,1,1]
	v_mfma_f32_16x16x32_bf16 v[98:101], v[66:69], v[18:21], v[98:101]
	v_mul_f32_e64 v44, v44, v118
	v_mul_f32_e64 v45, v45, v119
	ds_read2_b64 v[118:121], v185 offset0:64 offset1:72
	v_lshlrev_b32_e32 v114, 16, v167
	v_and_b32_e32 v115, 0xffff0000, v167
	v_mfma_f32_16x16x32_bf16 v[46:49], v[46:49], v[50:53], v[106:109]
	v_lshlrev_b32_e32 v122, 16, v163
	v_and_b32_e32 v123, 0xffff0000, v163
	v_pk_fma_f32 v[114:115], v[22:23], v[114:115], v[116:117] op_sel_hi:[0,1,1]
	v_mfma_f32_16x16x32_bf16 v[98:101], v[90:93], v[14:17], v[98:101]
	v_mul_f32_e64 v114, v114, v122
	v_mul_f32_e64 v115, v115, v123
	v_cvt_pk_bf16_f32 v44, v44, v45
	v_cvt_pk_bf16_f32 v45, v114, v115
	s_waitcnt lgkmcnt(0)
	v_lshlrev_b32_e32 v114, 16, v118
	v_and_b32_e32 v115, 0xffff0000, v118
	v_lshlrev_b32_e32 v106, 16, v136
	v_and_b32_e32 v107, 0xffff0000, v136
	v_pk_fma_f32 v[46:47], v[22:23], v[114:115], v[46:47] op_sel_hi:[0,1,1]
	v_pk_mul_f32 v[46:47], v[46:47], v[106:107]
	v_mfma_f32_16x16x32_bf16 v[98:101], v[58:61], v[10:13], v[98:101]
	v_cvt_pk_bf16_f32 v106, v46, v47
	v_lshlrev_b32_e32 v46, 16, v119
	v_and_b32_e32 v47, 0xffff0000, v119
	v_lshlrev_b32_e32 v108, 16, v137
	v_and_b32_e32 v109, 0xffff0000, v137
	v_pk_fma_f32 v[46:47], v[22:23], v[46:47], v[48:49] op_sel_hi:[0,1,1]
	v_pk_mul_f32 v[46:47], v[46:47], v[108:109]
	v_mfma_f32_16x16x32_bf16 v[94:97], v[74:77], v[18:21], v[94:97]
	v_cvt_pk_bf16_f32 v107, v46, v47
	v_mfma_f32_16x16x32_bf16 v[46:49], v[102:105], v[6:9], v[98:101]
	v_mfma_f32_16x16x32_bf16 v[46:49], v[110:113], v[50:53], v[46:49]
	s_nop 1
	v_lshlrev_b32_e32 v98, 16, v120
	v_and_b32_e32 v99, 0xffff0000, v120
	v_lshlrev_b32_e32 v100, 16, v134
	v_mfma_f32_16x16x32_bf16 v[94:97], v[66:69], v[14:17], v[94:97]
	v_and_b32_e32 v101, 0xffff0000, v134
	s_nop 0
	v_pk_fma_f32 v[46:47], v[22:23], v[98:99], v[46:47] op_sel_hi:[0,1,1]
	v_pk_mul_f32 v[46:47], v[46:47], v[100:101]
	v_mfma_f32_16x16x32_bf16 v[18:21], v[86:89], v[18:21], v[82:85]
	v_cvt_pk_bf16_f32 v108, v46, v47
	v_lshlrev_b32_e32 v46, 16, v121
	v_and_b32_e32 v47, 0xffff0000, v121
	v_mfma_f32_16x16x32_bf16 v[94:97], v[90:93], v[10:13], v[94:97]
	v_lshlrev_b32_e32 v110, 16, v135
	v_and_b32_e32 v111, 0xffff0000, v135
	v_pk_fma_f32 v[46:47], v[22:23], v[46:47], v[48:49] op_sel_hi:[0,1,1]
	v_mfma_f32_16x16x32_bf16 v[18:21], v[74:77], v[14:17], v[18:21]
	v_mul_f32_e64 v46, v46, v110
	v_mul_f32_e64 v47, v47, v111
	ds_read2_b64 v[98:101], v185 offset0:80 offset1:88
	v_cvt_pk_bf16_f32 v109, v46, v47
	v_mfma_f32_16x16x32_bf16 v[46:49], v[58:61], v[6:9], v[94:97]
	v_lshlrev_b32_e32 v84, 16, v133
	v_and_b32_e32 v85, 0xffff0000, v133
	v_mfma_f32_16x16x32_bf16 v[18:21], v[66:69], v[10:13], v[18:21]
	s_waitcnt lgkmcnt(0)
	v_lshlrev_b32_e32 v94, 16, v98
	v_and_b32_e32 v95, 0xffff0000, v98
	v_lshlrev_b32_e32 v96, 16, v132
	v_mfma_f32_16x16x32_bf16 v[46:49], v[102:105], v[50:53], v[46:49]
	v_and_b32_e32 v97, 0xffff0000, v132
	v_mfma_f32_16x16x32_bf16 v[14:17], v[86:89], v[14:17], v[78:81]
	v_mfma_f32_16x16x32_bf16 v[18:21], v[90:93], v[6:9], v[18:21]
	s_nop 4
	v_fma_f32 v46, v22, v94, v46
	v_fma_f32 v47, v22, v95, v47
	v_pk_mul_f32 v[46:47], v[46:47], v[96:97]
	v_mfma_f32_16x16x32_bf16 v[14:17], v[74:77], v[10:13], v[14:17]
	v_cvt_pk_bf16_f32 v82, v46, v47
	v_lshlrev_b32_e32 v46, 16, v99
	v_and_b32_e32 v47, 0xffff0000, v99
	v_mfma_f32_16x16x32_bf16 v[18:21], v[58:61], v[50:53], v[18:21]
	v_fma_f32 v46, v22, v46, v48
	v_fma_f32 v47, v22, v47, v49
	v_pk_mul_f32 v[46:47], v[46:47], v[84:85]
	v_lshlrev_b32_e32 v48, 16, v40
	v_cvt_pk_bf16_f32 v83, v46, v47
	v_lshlrev_b32_e32 v46, 16, v100
	v_and_b32_e32 v47, 0xffff0000, v100
	v_mfma_f32_16x16x32_bf16 v[14:17], v[66:69], v[6:9], v[14:17]
	v_and_b32_e32 v49, 0xffff0000, v40
	v_pk_fma_f32 v[18:19], v[22:23], v[46:47], v[18:19] op_sel_hi:[0,1,1]
	v_pk_mul_f32 v[18:19], v[18:19], v[48:49]
	ds_read2_b64 v[46:49], v185 offset0:96 offset1:104
	v_mfma_f32_16x16x32_bf16 v[10:13], v[86:89], v[10:13], v[70:73]
	v_lshlrev_b32_e32 v58, 16, v101
	v_and_b32_e32 v59, 0xffff0000, v101
	v_lshlrev_b32_e32 v40, 16, v41
	v_mfma_f32_16x16x32_bf16 v[14:17], v[90:93], v[50:53], v[14:17]
	v_and_b32_e32 v41, 0xffff0000, v41
	v_pk_fma_f32 v[20:21], v[22:23], v[58:59], v[20:21] op_sel_hi:[0,1,1]
	v_pk_mul_f32 v[20:21], v[20:21], v[40:41]
	v_mfma_f32_16x16x32_bf16 v[10:13], v[74:77], v[6:9], v[10:13]
	v_cvt_pk_bf16_f32 v18, v18, v19
	v_cvt_pk_bf16_f32 v19, v20, v21
	s_waitcnt lgkmcnt(0)
	v_lshlrev_b32_e32 v20, 16, v46
	v_and_b32_e32 v21, 0xffff0000, v46
	s_waitcnt vmcnt(3)
	v_lshlrev_b32_e32 v40, 16, v36
	v_and_b32_e32 v41, 0xffff0000, v36
	v_pk_fma_f32 v[14:15], v[22:23], v[20:21], v[14:15] op_sel_hi:[0,1,1]
	v_pk_mul_f32 v[14:15], v[14:15], v[40:41]
	v_mfma_f32_16x16x32_bf16 v[10:13], v[66:69], v[50:53], v[10:13]
	v_cvt_pk_bf16_f32 v20, v14, v15
	v_lshlrev_b32_e32 v14, 16, v47
	v_and_b32_e32 v15, 0xffff0000, v47
	v_lshlrev_b32_e32 v36, 16, v37
	v_and_b32_e32 v37, 0xffff0000, v37
	v_pk_fma_f32 v[14:15], v[22:23], v[14:15], v[16:17] op_sel_hi:[0,1,1]
	v_pk_mul_f32 v[14:15], v[14:15], v[36:37]
	v_mfma_f32_16x16x32_bf16 v[6:9], v[86:89], v[6:9], v[54:57]
	v_cvt_pk_bf16_f32 v21, v14, v15
	v_lshlrev_b32_e32 v14, 16, v48
	v_and_b32_e32 v15, 0xffff0000, v48
	s_waitcnt vmcnt(2)
	v_lshlrev_b32_e32 v16, 16, v32
	v_and_b32_e32 v17, 0xffff0000, v32
	v_pk_fma_f32 v[10:11], v[22:23], v[14:15], v[10:11] op_sel_hi:[0,1,1]
	v_pk_mul_f32 v[10:11], v[10:11], v[16:17]
	ds_read2_b64 v[14:17], v185 offset0:112 offset1:120
	v_lshlrev_b32_e32 v36, 16, v49
	v_and_b32_e32 v37, 0xffff0000, v49
	v_mfma_f32_16x16x32_bf16 v[6:9], v[74:77], v[50:53], v[6:9]
	v_lshlrev_b32_e32 v32, 16, v33
	v_and_b32_e32 v33, 0xffff0000, v33
	v_pk_fma_f32 v[12:13], v[22:23], v[36:37], v[12:13] op_sel_hi:[0,1,1]
	v_pk_mul_f32 v[12:13], v[12:13], v[32:33]
	v_cvt_pk_bf16_f32 v10, v10, v11
	v_cvt_pk_bf16_f32 v11, v12, v13
	s_waitcnt lgkmcnt(0)
	v_lshlrev_b32_e32 v12, 16, v14
	v_and_b32_e32 v13, 0xffff0000, v14
	s_waitcnt vmcnt(1)
	v_lshlrev_b32_e32 v32, 16, v28
	v_and_b32_e32 v33, 0xffff0000, v28
	v_pk_fma_f32 v[6:7], v[22:23], v[12:13], v[6:7] op_sel_hi:[0,1,1]
	v_pk_mul_f32 v[6:7], v[6:7], v[32:33]
	v_lshlrev_b32_e32 v14, 16, v29
	v_cvt_pk_bf16_f32 v12, v6, v7
	v_lshlrev_b32_e32 v6, 16, v15
	v_and_b32_e32 v7, 0xffff0000, v15
	v_and_b32_e32 v15, 0xffff0000, v29
	v_pk_fma_f32 v[6:7], v[22:23], v[6:7], v[8:9] op_sel_hi:[0,1,1]
	v_pk_mul_f32 v[6:7], v[6:7], v[14:15]
	v_lshlrev_b32_e32 v14, 16, v16
	v_cvt_pk_bf16_f32 v13, v6, v7
	v_mfma_f32_16x16x32_bf16 v[6:9], v[86:89], v[50:53], v[62:65]
	v_and_b32_e32 v15, 0xffff0000, v16
	s_waitcnt vmcnt(0)
	v_lshlrev_b32_e32 v28, 16, v24
	v_and_b32_e32 v29, 0xffff0000, v24
	v_lshlrev_b32_e32 v16, 16, v25
	s_nop 2
	v_pk_fma_f32 v[6:7], v[22:23], v[14:15], v[6:7] op_sel_hi:[0,1,1]
	v_lshlrev_b32_e32 v14, 16, v17
	v_and_b32_e32 v15, 0xffff0000, v17
	v_and_b32_e32 v17, 0xffff0000, v25
	v_pk_fma_f32 v[8:9], v[22:23], v[14:15], v[8:9] op_sel_hi:[0,1,1]
	v_pk_mul_f32 v[6:7], v[6:7], v[28:29]
	v_pk_mul_f32 v[8:9], v[8:9], v[16:17]
	v_cvt_pk_bf16_f32 v6, v6, v7
	v_cvt_pk_bf16_f32 v7, v8, v9
	v_lshl_add_u64 v[8:9], v[142:143], 0, s[12:13]
	global_store_dwordx2 v[8:9], v[26:27], off
	global_store_dwordx2 v[8:9], v[30:31], off offset:64
	global_store_dwordx2 v[8:9], v[34:35], off offset:128
	global_store_dwordx2 v[8:9], v[38:39], off offset:192
	global_store_dwordx2 v[8:9], v[130:131], off offset:256
	global_store_dwordx2 v[8:9], v[126:127], off offset:320
	global_store_dwordx2 v[8:9], v[42:43], off offset:384
	global_store_dwordx2 v[8:9], v[44:45], off offset:448
	global_store_dwordx2 v[8:9], v[106:107], off offset:512
	global_store_dwordx2 v[8:9], v[108:109], off offset:576
	global_store_dwordx2 v[8:9], v[82:83], off offset:640
	global_store_dwordx2 v[8:9], v[18:19], off offset:704
	global_store_dwordx2 v[8:9], v[20:21], off offset:768
	global_store_dwordx2 v[8:9], v[10:11], off offset:832
	global_store_dwordx2 v[8:9], v[12:13], off offset:896
	global_store_dwordx2 v[8:9], v[6:7], off offset:960
	s_waitcnt vmcnt(16)
	s_mov_b32 s12, s36
	s_barrier
	s_cbranch_vccnz .LBB0_2201
